# rstd-in-LDS for all four norm-folded GEMM epilogues (phases 1,6,8,12): per-phase preload into 4KB static LDS replaces per-unit row-sum loads + bpermute reduction
# speedup vs baseline: 1.0017x; 1.0017x over previous
;     __device__ __forceinline__ void operator()(const f32x4 (&acc)[2][2][4][2], const Unit& u, int wr, int wc, int fr, int fq, const float (&)[8]) const {
;     ...
;             for (int m = 0; m < 4; ++m) { const int row = row0 + ai * HALF + m * 16;
;                 if (SLOTS == 1) ep[ai * 4 + m] = ss[row];
; template <class Epi>
; __device__ __forceinline__ void gemm_phase(LAS unsigned char* lds, const Gemm g, const StaticOrder& S, const Epi& E) {
;     const int tid = threadIdx.x, wid = __builtin_amdgcn_readfirstlane(tid >> 6), lane = tid & 63, wr = wid >> 2, wc = wid & 3, fr = lane & 15, fq = lane >> 4;
;     const int K = g.K, nt = K / BK, lda = g.lda;
;     unsigned voffA[2], voffB[2];
; #pragma unroll
;     for (int i = 0; i < 2; ++i) { int R, C; stage_rc(tid * 16 + i * 8192, R, C); const int Rb = Epi::PERM ? ((R & ~31) + perm32(R & 31)) : R;
;         voffA[i] = (unsigned)(R * lda + C) * 2u; voffB[i] = (unsigned)(Rb * K + C) * 2u; }
;     const size_t kstep = (size_t)(BK * 2);
;     const size_t hstepA = (size_t)HALF * lda * 2, hstepB = (size_t)HALF * K * 2;
;     const size_t tstepA = 2 * hstepA, tstepB = 2 * hstepB;
;     const unsigned ldsw = (unsigned)wid * 1024u;
;     const int aoff = lds_byte(wr * 64 + fr, fq * 8), boff = lds_byte(wc * 32 + fr, fq * 8);
;     ...
;     Unit cur, nxt; int ui = 0;
;     if (!S.next(0, cur)) return;
;     ...
;     for (int q_ = 0; q_ < ((S.c >> 3) & 3); ++q_) __builtin_amdgcn_s_sleep(100);
;     ...
;     f32x4 acc[2][2][4][2];
; #pragma unroll
;     for (int a = 0; a < 2; ++a)
; #pragma unroll
;         for (int b = 0; b < 2; ++b)
; #pragma unroll
;             for (int m = 0; m < 4; ++m)
; #pragma unroll
;                 for (int n = 0; n < 2; ++n) acc[a][b][m][n] = (f32x4){0.f, 0.f, 0.f, 0.f};
;     bf16x8 At[4][2], B0[2][2], B1[2][2]; float epre[8];
; #pragma unroll
;     for (int q_ = 0; q_ < 8; ++q_) epre[q_] = 0.f;
;     const char* cA = (const char*)g.A + (size_t)cur.pm * tstepA; const char* cB = (const char*)g.Bt + (size_t)cur.pn * tstepB;
;     PG8_STAGE(PG8_SB(0, 0), cB, voffB); PG8_STAGE(PG8_SA(0, 0), cA, voffA); PG8_STAGE(PG8_SB(0, 1), cB + hstepB, voffB); PG8_STAGE(PG8_SA(0, 1), cA + hstepA, voffA);
;     if (wr == 1) PG8_BAR;
;     PG8_WAIT_V(4); PG8_BAR;
;     PG8_STAGE(PG8_SB(1, 0), cB + kstep, voffB); PG8_STAGE(PG8_SA(1, 0), cA + kstep, voffA); PG8_STAGE(PG8_SB(1, 1), cB + hstepB + kstep, voffB);
;     PG8_WAIT_V(6); PG8_BAR;
.LBB0_196:
	s_add_u32 s96, s74, 0x143c0000
	s_addc_u32 s97, s75, 0
	s_add_u32 s2, s74, 0x3bc0000
	s_addc_u32 s3, s75, 0
	v_writelane_b32 v251, s2, 52
	s_cmp_lt_i32 s40, 2
	s_nop 0
	v_writelane_b32 v251, s3, 53
	s_cselect_b64 s[2:3], -1, 0
	s_and_b64 s[0:1], s[2:3], s[0:1]
	s_andn2_b64 vcc, exec, s[0:1]
	v_writelane_b32 v251, s40, 54
	s_nop 1
	v_writelane_b32 v251, s41, 55
	s_cbranch_vccnz .LBB0_214
	s_and_b32 s50, s93, 7
	s_lshl_b32 s50, s50, 5
	s_bfe_u32 s47, s93, 0x30003
	s_add_i32 s50, s50, s47
	s_add_u32 s48, s74, 0x3a80000
	s_addc_u32 s49, s75, 0
	s_mov_b32 s46, 0x800000
	v_lshrrev_b32_e32 v225, 8, v152
	v_and_b32_e32 v224, 0xff, v152
	v_lshl_add_u32 v223, v225, 3, s50
	v_lshl_or_b32 v222, v223, 8, v224
	v_add_u32_e32 v221, 0x1000, v222
	v_lshlrev_b32_e32 v220, 2, v152
	v_add_u32_e32 v220, 0x20010, v220
	v_lshlrev_b32_e32 v222, 2, v222
	v_lshlrev_b32_e32 v221, 2, v221
	v_mov_b32_e32 v219, 0x358637bd
	global_load_dword v214, v222, s[48:49]
	global_load_dword v213, v221, s[48:49]
	s_waitcnt vmcnt(0)
	v_fmamk_f32 v214, v214, 0x3a800000, v219
	v_mul_f32_e32 v218, 0x4b800000, v214
	v_cmp_gt_f32_e32 vcc, s46, v214
	s_nop 1
	v_cndmask_b32_e32 v217, v214, v218, vcc
	v_rsq_f32_e32 v216, v217
	s_nop 0
	v_mul_f32_e32 v215, 0x45800000, v216
	v_cndmask_b32_e32 v215, v216, v215, vcc
	ds_write_b32 v220, v215
	v_fmamk_f32 v213, v213, 0x3a800000, v219
	v_mul_f32_e32 v218, 0x4b800000, v213
	v_cmp_gt_f32_e32 vcc, s46, v213
	s_nop 1
	v_cndmask_b32_e32 v217, v213, v218, vcc
	v_rsq_f32_e32 v216, v217
	s_nop 0
	v_mul_f32_e32 v215, 0x45800000, v216
	v_cndmask_b32_e32 v215, v216, v215, vcc
	ds_write_b32 v220, v215 offset:2048
	s_waitcnt lgkmcnt(0)
	s_barrier
	s_cmpk_gt_i32 s93, 0x14ff
	v_readfirstlane_b32 s26, v152
	s_cbranch_scc1 .LBB0_214
	v_lshrrev_b32_e32 v0, 5, v152
	v_lshrrev_b32_e32 v2, 1, v152
	v_and_b32_e32 v0, 4, v0
	v_bfe_u32 v1, v152, 2, 2
	v_and_b32_e32 v11, 24, v2
	v_or3_b32 v0, v0, v1, v11
	v_lshlrev_b32_e32 v1, 4, v152
	v_add_u32_e32 v8, 0x2000, v1
	v_lshrrev_b32_e32 v2, 7, v8
	s_movk_i32 s0, 0xe0
	v_and_b32_e32 v4, 32, v152
	v_and_or_b32 v3, v2, s0, v0
	v_bitop3_b32 v9, v1, v4, 48 bitop3:0x6c
	v_and_b32_e32 v10, 64, v152
	v_bfe_u32 v12, v152, 2, 4
	s_movk_i32 s0, 0xf0
	v_or_b32_e32 v1, v9, v10
	v_and_or_b32 v2, v2, s0, v12
	v_lshl_or_b32 v130, v2, 11, v1
	v_lshrrev_b32_e32 v2, 3, v152
	s_movk_i32 s0, 0x60
	v_and_or_b32 v0, v2, s0, v0
	s_movk_i32 s0, 0x70
	s_ashr_i32 s28, s93, 31
	v_lshl_or_b32 v132, v0, 11, v1
	v_and_or_b32 v0, v2, s0, v12
	s_lshr_b32 s0, s28, 29
	s_add_i32 s0, s93, s0
	s_lshr_b32 s6, s26, 6
	s_ashr_i32 s7, s0, 3
	s_and_b32 s0, s0, -8
	s_lshr_b32 s1, s26, 8
	s_lshl_b32 s27, s6, 10
	s_sub_i32 s0, s93, s0
	s_cmp_lt_i32 s0, 0
	s_movk_i32 s29, 0x2a1
	s_cselect_b32 s8, s29, 0x2a0
	s_mul_i32 s0, s0, s8
	s_add_i32 s0, s0, s7
	s_mul_hi_i32 s7, s0, 0x30c30c31
	s_lshr_b32 s8, s7, 31
	s_ashr_i32 s7, s7, 5
	s_add_i32 s7, s7, s8
	s_lshl_b32 s8, s7, 3
	s_mulk_i32 s7, 0xa8
	s_sub_i32 s7, s0, s7
	s_sext_i32_i16 s0, s7
	s_bfe_u32 s0, s0, 0x3001c
	s_add_i32 s9, s7, s0
	s_sext_i32_i16 s0, s9
	s_and_b32 s9, s9, 0xfff8
	s_sub_i32 s7, s7, s9
	s_sext_i32_i16 s7, s7
	s_lshr_b32 s0, s0, 3
	s_add_i32 s18, s8, s7
	s_ashr_i32 s19, s18, 31
	s_bfe_i64 s[10:11], s[0:1], 0x100000
	s_lshl_b64 s[8:9], s[18:19], 19
	s_lshl_b64 s[10:11], s[10:11], 19
	s_add_u32 s22, s74, s10
	s_addc_u32 s23, s75, s11
	s_add_i32 s30, s27, 0
	s_add_i32 m0, s30, 0x10000
	v_lshl_or_b32 v128, v3, 11, v1
	global_load_lds_dwordx4 v132, s[22:23]
	s_add_i32 m0, s30, 0x12000
	s_add_u32 s20, s76, s8
	v_lshl_or_b32 v134, v0, 11, v1
	global_load_lds_dwordx4 v128, s[22:23]
	s_addc_u32 s21, s77, s9
	s_mov_b32 m0, s30
	s_add_i32 s31, s30, 0x2000
	global_load_lds_dwordx4 v134, s[20:21]
	s_mov_b32 m0, s31
	s_add_u32 s8, s22, 0x40000
	global_load_lds_dwordx4 v130, s[20:21]
	s_addc_u32 s9, s23, 0
	s_add_i32 m0, s30, 0x14000
	v_mov_b32_e32 v133, 0
	global_load_lds_dwordx4 v132, s[8:9]
	s_add_i32 m0, s30, 0x16000
	v_mov_b32_e32 v129, v133
	global_load_lds_dwordx4 v128, s[8:9]
	s_add_u32 s8, s20, 0x40000
	s_addc_u32 s9, s21, 0
	s_add_i32 s33, s30, 0x4000
	s_mov_b32 m0, s33
	s_add_i32 s34, s30, 0x6000
	global_load_lds_dwordx4 v134, s[8:9]
	s_mov_b32 m0, s34
	v_mov_b32_e32 v135, v133
	global_load_lds_dwordx4 v130, s[8:9]
	v_mov_b32_e32 v131, v133
	s_mov_b32 s35, 0
	v_lshl_add_u64 v[6:7], s[22:23], 0, v[132:133]
	v_lshl_add_u64 v[4:5], s[22:23], 0, v[128:129]
	v_lshl_add_u64 v[2:3], s[20:21], 0, v[134:135]
	s_cmp_lg_u32 s1, 1
	v_lshl_add_u64 v[0:1], s[20:21], 0, v[130:131]
	s_cbranch_scc1 .LBB0_200
	s_barrier

; #define PG8_STAGE(bufoff, gbase, voff) do { _Pragma("unroll") for (int _i = 0; _i < 2; ++_i) \
;         __builtin_amdgcn_global_load_lds((const unsigned*)((const char*)(gbase) + (voff)[_i]), (LAS unsigned*)(lds + (bufoff) + ldsw + _i * 8192), 16, 0, 0); } while (0)
; #define PG8_LDA(dst, b, h) do { _Pragma("unroll") for (int m = 0; m < 4; ++m) _Pragma("unroll") for (int k = 0; k < 2; ++k) dst[m][k] = *(const LAS bf16x8*)(lds + PG8_SA(b, h) + aoff + m * 2048 + k * 1024); } while (0)
; #define PG8_LDB(dst, b, h) do { _Pragma("unroll") for (int n = 0; n < 2; ++n) _Pragma("unroll") for (int k = 0; k < 2; ++k) dst[n][k] = *(const LAS bf16x8*)(lds + PG8_SB(b, h) + boff + n * 2048 + k * 1024); } while (0)
; #define PG8_MMA(ai, bj, At, Bt) do { __builtin_amdgcn_s_setprio(1); _Pragma("unroll") for (int m = 0; m < 4; ++m) _Pragma("unroll") for (int n = 0; n < 2; ++n) _Pragma("unroll") for (int k = 0; k < 2; ++k) \
;         acc[ai][bj][m][n] = __builtin_amdgcn_mfma_f32_16x16x32_bf16(Bt[n][k], At[m][k], acc[ai][bj][m][n], 0, 0, 0); __builtin_amdgcn_s_setprio(0); } while (0)
; #define PG8_WAIT_L(n) asm volatile("s_waitcnt lgkmcnt(" #n ")" ::: "memory")
; #define PG8_BAR __builtin_amdgcn_s_barrier()
; #define PG8_SCHED __builtin_amdgcn_sched_barrier(0)
; template <class Epi>
; __device__ __forceinline__ void gemm_phase(LAS unsigned char* lds, const Gemm g, const StaticOrder& S, const Epi& E) {
;     ...
;             PG8_LDB(B0, 0, 0); PG8_SCHED; PG8_LDA(At, 0, 0); PG8_STAGE(PG8_SA(1, 1), a1 + hstepA, voffA);
;             PG8_WAIT_L(8); PG8_BAR; PG8_WAIT_L(0); PG8_MMA(0, 0, At, B0); PG8_BAR; PG8_SCHED;
;             PG8_LDB(B1, 0, 1); PG8_STAGE(PG8_SB(0, 0), b2, voffB);
;             PG8_BAR; PG8_WAIT_L(0); PG8_MMA(0, 1, At, B1); PG8_BAR;
;             PG8_LDA(At, 0, 1); PG8_STAGE(PG8_SA(0, 0), a2, voffA);
;             PG8_BAR; PG8_WAIT_L(0); PG8_MMA(1, 0, At, B0); PG8_BAR; PG8_SCHED;
.LBB0_205:
	ds_read_b128 v[146:149], v170
	ds_read_b128 v[154:157], v170 offset:1024
	ds_read_b128 v[158:161], v170 offset:2048
	ds_read_b128 v[162:165], v170 offset:3072
	s_add_u32 s22, s20, 0xfffc0080
	s_addc_u32 s23, s21, -1
	s_cmp_eq_u32 s47, 12
	s_cselect_b32 s25, s13, s23
	s_cselect_b32 s24, s19, s22
	s_cselect_b32 s23, s11, s46
	s_cselect_b32 s22, s44, s45
	v_lshl_add_u64 v[150:151], s[20:21], 0, v[138:139]
	s_add_i32 m0, s30, 0xc000
	s_waitcnt vmcnt(0)
	ds_read_b128 v[174:177], v171
	ds_read_b128 v[178:181], v171 offset:1024
	ds_read_b128 v[182:185], v171 offset:2048
	ds_read_b128 v[186:189], v171 offset:3072
	ds_read_b128 v[190:193], v171 offset:4096
	ds_read_b128 v[194:197], v171 offset:5120
	ds_read_b128 v[198:201], v171 offset:6144
	ds_read_b128 v[202:205], v171 offset:7168
	global_load_lds_dwordx4 v[150:151], off
	v_lshl_add_u64 v[150:151], s[20:21], 0, v[140:141]
	s_add_i32 m0, s30, 0xe000
	s_nop 0
	global_load_lds_dwordx4 v[150:151], off
	s_waitcnt lgkmcnt(8)
	s_barrier
	s_waitcnt lgkmcnt(0)
	s_setprio 1
	s_waitcnt lgkmcnt(0)
	v_mfma_f32_16x16x32_bf16 v[76:79], v[146:149], v[174:177], v[76:79]
	v_mfma_f32_16x16x32_bf16 v[64:67], v[158:161], v[174:177], v[64:67]
	v_mfma_f32_16x16x32_bf16 v[60:63], v[146:149], v[182:185], v[60:63]
	v_mfma_f32_16x16x32_bf16 v[56:59], v[158:161], v[182:185], v[56:59]
	v_mfma_f32_16x16x32_bf16 v[48:51], v[146:149], v[190:193], v[48:51]
	v_mfma_f32_16x16x32_bf16 v[40:43], v[158:161], v[190:193], v[40:43]
	v_mfma_f32_16x16x32_bf16 v[36:39], v[146:149], v[198:201], v[36:39]
	v_mfma_f32_16x16x32_bf16 v[32:35], v[158:161], v[198:201], v[32:35]
	v_mfma_f32_16x16x32_bf16 v[76:79], v[154:157], v[178:181], v[76:79]
	v_mfma_f32_16x16x32_bf16 v[64:67], v[162:165], v[178:181], v[64:67]
	v_mfma_f32_16x16x32_bf16 v[60:63], v[154:157], v[186:189], v[60:63]
	v_mfma_f32_16x16x32_bf16 v[56:59], v[162:165], v[186:189], v[56:59]
	v_mfma_f32_16x16x32_bf16 v[48:51], v[154:157], v[194:197], v[48:51]
	v_mfma_f32_16x16x32_bf16 v[40:43], v[162:165], v[194:197], v[40:43]
	v_mfma_f32_16x16x32_bf16 v[36:39], v[154:157], v[202:205], v[36:39]
	v_mfma_f32_16x16x32_bf16 v[32:35], v[162:165], v[202:205], v[32:35]
	s_setprio 0
	s_barrier
	s_add_i32 s48, s39, s27
	v_lshl_add_u64 v[150:151], s[22:23], 0, v[132:133]
	s_mov_b32 m0, s48
	ds_read_b128 v[206:209], v172
	ds_read_b128 v[210:213], v172 offset:1024
	ds_read_b128 v[214:217], v172 offset:2048
	ds_read_b128 v[218:221], v172 offset:3072
	global_load_lds_dwordx4 v[150:151], off
	v_lshl_add_u64 v[166:167], s[22:23], 0, v[128:129]
	s_add_i32 m0, s48, 0x2000
	s_nop 0
	global_load_lds_dwordx4 v[166:167], off
	s_barrier
	s_waitcnt lgkmcnt(0)
	s_setprio 1
	s_waitcnt lgkmcnt(0)
	v_mfma_f32_16x16x32_bf16 v[124:127], v[206:209], v[174:177], v[124:127]
	v_mfma_f32_16x16x32_bf16 v[120:123], v[214:217], v[174:177], v[120:123]
	v_mfma_f32_16x16x32_bf16 v[116:119], v[206:209], v[182:185], v[116:119]
	v_mfma_f32_16x16x32_bf16 v[112:115], v[214:217], v[182:185], v[112:115]
	v_mfma_f32_16x16x32_bf16 v[108:111], v[206:209], v[190:193], v[108:111]
	v_mfma_f32_16x16x32_bf16 v[104:107], v[214:217], v[190:193], v[104:107]
	v_mfma_f32_16x16x32_bf16 v[100:103], v[206:209], v[198:201], v[100:103]
	v_mfma_f32_16x16x32_bf16 v[96:99], v[214:217], v[198:201], v[96:99]
	v_mfma_f32_16x16x32_bf16 v[124:127], v[210:213], v[178:181], v[124:127]
	v_mfma_f32_16x16x32_bf16 v[120:123], v[218:221], v[178:181], v[120:123]
	v_mfma_f32_16x16x32_bf16 v[116:119], v[210:213], v[186:189], v[116:119]
	v_mfma_f32_16x16x32_bf16 v[112:115], v[218:221], v[186:189], v[112:115]
	v_mfma_f32_16x16x32_bf16 v[108:111], v[210:213], v[194:197], v[108:111]
	v_mfma_f32_16x16x32_bf16 v[104:107], v[218:221], v[194:197], v[104:107]
	v_mfma_f32_16x16x32_bf16 v[100:103], v[210:213], v[202:205], v[100:103]
	v_mfma_f32_16x16x32_bf16 v[96:99], v[218:221], v[202:205], v[96:99]
	s_setprio 0
	s_mov_b32 m0, s30
	v_lshl_add_u64 v[222:223], s[24:25], 0, v[134:135]
	s_barrier
	ds_read_b128 v[174:177], v171 offset:16384
	ds_read_b128 v[178:181], v171 offset:17408
	ds_read_b128 v[182:185], v171 offset:18432
	ds_read_b128 v[186:189], v171 offset:19456
	ds_read_b128 v[190:193], v171 offset:20480
	ds_read_b128 v[194:197], v171 offset:21504
	ds_read_b128 v[198:201], v171 offset:22528
	ds_read_b128 v[202:205], v171 offset:23552
	global_load_lds_dwordx4 v[222:223], off
	v_lshl_add_u64 v[224:225], s[24:25], 0, v[130:131]
	s_mov_b32 m0, s31
	s_nop 0
	global_load_lds_dwordx4 v[224:225], off
	s_barrier
	s_waitcnt lgkmcnt(0)
	s_setprio 1
	s_waitcnt lgkmcnt(0)
	v_mfma_f32_16x16x32_bf16 v[28:31], v[146:149], v[174:177], v[28:31]
	v_mfma_f32_16x16x32_bf16 v[24:27], v[158:161], v[174:177], v[24:27]
	v_mfma_f32_16x16x32_bf16 v[20:23], v[146:149], v[182:185], v[20:23]
	v_mfma_f32_16x16x32_bf16 v[16:19], v[158:161], v[182:185], v[16:19]
	v_mfma_f32_16x16x32_bf16 v[12:15], v[146:149], v[190:193], v[12:15]
	v_mfma_f32_16x16x32_bf16 v[8:11], v[158:161], v[190:193], v[8:11]
	v_mfma_f32_16x16x32_bf16 v[4:7], v[146:149], v[198:201], v[4:7]
	v_mfma_f32_16x16x32_bf16 v[0:3], v[158:161], v[198:201], v[0:3]
	v_mfma_f32_16x16x32_bf16 v[28:31], v[154:157], v[178:181], v[28:31]
	v_mfma_f32_16x16x32_bf16 v[24:27], v[162:165], v[178:181], v[24:27]
	v_mfma_f32_16x16x32_bf16 v[20:23], v[154:157], v[186:189], v[20:23]
	v_mfma_f32_16x16x32_bf16 v[16:19], v[162:165], v[186:189], v[16:19]
	v_mfma_f32_16x16x32_bf16 v[12:15], v[154:157], v[194:197], v[12:15]
	v_mfma_f32_16x16x32_bf16 v[8:11], v[162:165], v[194:197], v[8:11]
	v_mfma_f32_16x16x32_bf16 v[4:7], v[154:157], v[202:205], v[4:7]
	v_mfma_f32_16x16x32_bf16 v[0:3], v[162:165], v[202:205], v[0:3]
	s_setprio 0
	s_barrier
; #define PG8_STAGE(bufoff, gbase, voff) do { _Pragma("unroll") for (int _i = 0; _i < 2; ++_i) \
;         __builtin_amdgcn_global_load_lds((const unsigned*)((const char*)(gbase) + (voff)[_i]), (LAS unsigned*)(lds + (bufoff) + ldsw + _i * 8192), 16, 0, 0); } while (0)
; #define PG8_LDA(dst, b, h) do { _Pragma("unroll") for (int m = 0; m < 4; ++m) _Pragma("unroll") for (int k = 0; k < 2; ++k) dst[m][k] = *(const LAS bf16x8*)(lds + PG8_SA(b, h) + aoff + m * 2048 + k * 1024); } while (0)
; #define PG8_LDB(dst, b, h) do { _Pragma("unroll") for (int n = 0; n < 2; ++n) _Pragma("unroll") for (int k = 0; k < 2; ++k) dst[n][k] = *(const LAS bf16x8*)(lds + PG8_SB(b, h) + boff + n * 2048 + k * 1024); } while (0)
; #define PG8_MMA(ai, bj, At, Bt) do { __builtin_amdgcn_s_setprio(1); _Pragma("unroll") for (int m = 0; m < 4; ++m) _Pragma("unroll") for (int n = 0; n < 2; ++n) _Pragma("unroll") for (int k = 0; k < 2; ++k) \
;         acc[ai][bj][m][n] = __builtin_amdgcn_mfma_f32_16x16x32_bf16(Bt[n][k], At[m][k], acc[ai][bj][m][n], 0, 0, 0); __builtin_amdgcn_s_setprio(0); } while (0)
; #define PG8_WAIT_V(n) asm volatile("s_waitcnt vmcnt(" #n ")" ::: "memory")
; #define PG8_WAIT_L(n) asm volatile("s_waitcnt lgkmcnt(" #n ")" ::: "memory")
; #define PG8_BAR __builtin_amdgcn_s_barrier()
; #define PG8_SCHED __builtin_amdgcn_sched_barrier(0)
; template <class Epi>
; __device__ __forceinline__ void gemm_phase(LAS unsigned char* lds, const Gemm g, const StaticOrder& S, const Epi& E) {
;     ...
;             PG8_STAGE(PG8_SB(0, 1), b2 + hstepB, voffB);
;             PG8_WAIT_V(6); PG8_BAR; PG8_MMA(1, 1, At, B1); PG8_BAR;
;             PG8_LDB(B0, 1, 0); PG8_SCHED; PG8_LDA(At, 1, 0); PG8_STAGE(PG8_SA(0, 1), a2 + hstepA, voffA);
;             PG8_WAIT_L(8); PG8_BAR; PG8_WAIT_L(0); PG8_MMA(0, 0, At, B0); PG8_BAR; PG8_SCHED;
;             PG8_LDB(B1, 1, 1); PG8_STAGE(PG8_SB(1, 0), b3, voffB);
;             PG8_BAR; PG8_WAIT_L(0); PG8_MMA(0, 1, At, B1); PG8_BAR;
;             PG8_LDA(At, 1, 1); PG8_STAGE(PG8_SA(1, 0), a3, voffA);
	s_add_u32 s48, s22, 0x40000
	s_addc_u32 s49, s23, 0
	s_add_i32 s50, s40, s27
	v_lshl_add_u64 v[146:147], s[48:49], 0, v[132:133]
	s_mov_b32 m0, s50
	s_nop 0
	global_load_lds_dwordx4 v[146:147], off
	v_lshl_add_u64 v[146:147], s[48:49], 0, v[128:129]
	s_add_i32 m0, s50, 0x2000
	s_nop 0
	global_load_lds_dwordx4 v[146:147], off
	s_waitcnt vmcnt(6)
	s_barrier
	s_setprio 1
	v_mfma_f32_16x16x32_bf16 v[92:95], v[206:209], v[174:177], v[92:95]
	v_mfma_f32_16x16x32_bf16 v[88:91], v[214:217], v[174:177], v[88:91]
	v_mfma_f32_16x16x32_bf16 v[84:87], v[206:209], v[182:185], v[84:87]
	v_mfma_f32_16x16x32_bf16 v[80:83], v[214:217], v[182:185], v[80:83]
	v_mfma_f32_16x16x32_bf16 v[72:75], v[206:209], v[190:193], v[72:75]
	v_mfma_f32_16x16x32_bf16 v[68:71], v[214:217], v[190:193], v[68:71]
	v_mfma_f32_16x16x32_bf16 v[52:55], v[206:209], v[198:201], v[52:55]
	v_mfma_f32_16x16x32_bf16 v[44:47], v[214:217], v[198:201], v[44:47]
	v_mfma_f32_16x16x32_bf16 v[92:95], v[210:213], v[178:181], v[92:95]
	v_mfma_f32_16x16x32_bf16 v[88:91], v[218:221], v[178:181], v[88:91]
	v_mfma_f32_16x16x32_bf16 v[84:87], v[210:213], v[186:189], v[84:87]
	v_mfma_f32_16x16x32_bf16 v[80:83], v[218:221], v[186:189], v[80:83]
	v_mfma_f32_16x16x32_bf16 v[72:75], v[210:213], v[194:197], v[72:75]
	v_mfma_f32_16x16x32_bf16 v[68:71], v[218:221], v[194:197], v[68:71]
	v_mfma_f32_16x16x32_bf16 v[52:55], v[210:213], v[202:205], v[52:55]
	v_mfma_f32_16x16x32_bf16 v[44:47], v[218:221], v[202:205], v[44:47]
	s_setprio 0
	s_add_i32 s48, 0, 0x18000
	v_add_u32_e32 v162, s48, v168
	s_barrier
	ds_read_b128 v[146:149], v162
	ds_read_b128 v[154:157], v162 offset:1024
	ds_read_b128 v[158:161], v162 offset:2048
	ds_read_b128 v[162:165], v162 offset:3072
	s_add_u32 s24, s24, 0x40000
	s_addc_u32 s25, s25, 0
	s_mov_b32 m0, s33
	v_lshl_add_u64 v[206:207], s[24:25], 0, v[134:135]
	ds_read_b128 v[174:177], v171 offset:32768
	ds_read_b128 v[178:181], v171 offset:33792
	ds_read_b128 v[182:185], v171 offset:34816
	ds_read_b128 v[186:189], v171 offset:35840
	ds_read_b128 v[190:193], v171 offset:36864
	ds_read_b128 v[194:197], v171 offset:37888
	ds_read_b128 v[198:201], v171 offset:38912
	ds_read_b128 v[202:205], v171 offset:39936
	global_load_lds_dwordx4 v[206:207], off
	v_lshl_add_u64 v[206:207], s[24:25], 0, v[130:131]
	s_mov_b32 m0, s34
	s_nop 0
	global_load_lds_dwordx4 v[206:207], off
	s_waitcnt lgkmcnt(8)
	s_barrier
	s_waitcnt lgkmcnt(0)
	s_setprio 1
	s_waitcnt lgkmcnt(0)
	v_mfma_f32_16x16x32_bf16 v[76:79], v[146:149], v[174:177], v[76:79]
	v_mfma_f32_16x16x32_bf16 v[64:67], v[158:161], v[174:177], v[64:67]
	v_mfma_f32_16x16x32_bf16 v[60:63], v[146:149], v[182:185], v[60:63]
	v_mfma_f32_16x16x32_bf16 v[56:59], v[158:161], v[182:185], v[56:59]
	v_mfma_f32_16x16x32_bf16 v[48:51], v[146:149], v[190:193], v[48:51]
	v_mfma_f32_16x16x32_bf16 v[40:43], v[158:161], v[190:193], v[40:43]
	v_mfma_f32_16x16x32_bf16 v[36:39], v[146:149], v[198:201], v[36:39]
	v_mfma_f32_16x16x32_bf16 v[32:35], v[158:161], v[198:201], v[32:35]
	v_mfma_f32_16x16x32_bf16 v[76:79], v[154:157], v[178:181], v[76:79]
	v_mfma_f32_16x16x32_bf16 v[64:67], v[162:165], v[178:181], v[64:67]
	v_mfma_f32_16x16x32_bf16 v[60:63], v[154:157], v[186:189], v[60:63]
	v_mfma_f32_16x16x32_bf16 v[56:59], v[162:165], v[186:189], v[56:59]
	v_mfma_f32_16x16x32_bf16 v[48:51], v[154:157], v[194:197], v[48:51]
	v_mfma_f32_16x16x32_bf16 v[40:43], v[162:165], v[194:197], v[40:43]
	v_mfma_f32_16x16x32_bf16 v[36:39], v[154:157], v[202:205], v[36:39]
	v_mfma_f32_16x16x32_bf16 v[32:35], v[162:165], v[202:205], v[32:35]
	s_setprio 0
	s_barrier
	s_add_i32 s24, 0, 0x1c000
	s_add_i32 s25, s48, s27
	v_add_u32_e32 v218, s24, v168
	v_lshl_add_u64 v[150:151], v[150:151], 0, s[6:7]
	s_mov_b32 m0, s25
	ds_read_b128 v[206:209], v218
	ds_read_b128 v[210:213], v218 offset:1024
	ds_read_b128 v[214:217], v218 offset:2048
	ds_read_b128 v[218:221], v218 offset:3072
	global_load_lds_dwordx4 v[150:151], off
	v_lshl_add_u64 v[150:151], v[166:167], 0, s[6:7]
	s_add_i32 m0, s25, 0x2000
	s_nop 0
	global_load_lds_dwordx4 v[150:151], off
	s_barrier
	s_waitcnt lgkmcnt(0)
	s_setprio 1
	s_waitcnt lgkmcnt(0)
	v_mfma_f32_16x16x32_bf16 v[124:127], v[206:209], v[174:177], v[124:127]
	v_mfma_f32_16x16x32_bf16 v[120:123], v[214:217], v[174:177], v[120:123]
	v_mfma_f32_16x16x32_bf16 v[116:119], v[206:209], v[182:185], v[116:119]
	v_mfma_f32_16x16x32_bf16 v[112:115], v[214:217], v[182:185], v[112:115]
	v_mfma_f32_16x16x32_bf16 v[108:111], v[206:209], v[190:193], v[108:111]
	v_mfma_f32_16x16x32_bf16 v[104:107], v[214:217], v[190:193], v[104:107]
	v_mfma_f32_16x16x32_bf16 v[100:103], v[206:209], v[198:201], v[100:103]
	v_mfma_f32_16x16x32_bf16 v[96:99], v[214:217], v[198:201], v[96:99]
	v_mfma_f32_16x16x32_bf16 v[124:127], v[210:213], v[178:181], v[124:127]
	v_mfma_f32_16x16x32_bf16 v[120:123], v[218:221], v[178:181], v[120:123]
	v_mfma_f32_16x16x32_bf16 v[116:119], v[210:213], v[186:189], v[116:119]
	v_mfma_f32_16x16x32_bf16 v[112:115], v[218:221], v[186:189], v[112:115]
	v_mfma_f32_16x16x32_bf16 v[108:111], v[210:213], v[194:197], v[108:111]
	v_mfma_f32_16x16x32_bf16 v[104:107], v[218:221], v[194:197], v[104:107]
	v_mfma_f32_16x16x32_bf16 v[100:103], v[210:213], v[202:205], v[100:103]
	v_mfma_f32_16x16x32_bf16 v[96:99], v[218:221], v[202:205], v[96:99]
	s_setprio 0
	s_mov_b32 m0, s36
	v_lshl_add_u64 v[150:151], v[222:223], 0, s[6:7]
	s_barrier
	ds_read_b128 v[174:177], v171 offset:49152
	ds_read_b128 v[178:181], v171 offset:50176
	ds_read_b128 v[182:185], v171 offset:51200
	ds_read_b128 v[186:189], v171 offset:52224
	ds_read_b128 v[190:193], v171 offset:53248
	ds_read_b128 v[194:197], v171 offset:54272
	ds_read_b128 v[198:201], v171 offset:55296
	ds_read_b128 v[202:205], v171 offset:56320
	global_load_lds_dwordx4 v[150:151], off
	v_lshl_add_u64 v[150:151], v[224:225], 0, s[6:7]
	s_mov_b32 m0, s37
	s_nop 0
	global_load_lds_dwordx4 v[150:151], off
	s_barrier
; __device__ __forceinline__ unsigned pk2(float lo, float hi) { const f32x2 v = (f32x2){lo, hi}; const bf16x2_t b = __builtin_convertvector(v, bf16x2_t); return __builtin_bit_cast(unsigned, b); }
; #define PG8_STAGE(bufoff, gbase, voff) do { _Pragma("unroll") for (int _i = 0; _i < 2; ++_i) \
;         __builtin_amdgcn_global_load_lds((const unsigned*)((const char*)(gbase) + (voff)[_i]), (LAS unsigned*)(lds + (bufoff) + ldsw + _i * 8192), 16, 0, 0); } while (0)
;     __device__ __forceinline__ void operator()(const f32x4 (&acc)[2][2][4][2], const Unit& u, int wr, int wc, int fr, int fq, const float (&)[8]) const {
;     ...
;         if (DT && u.pn == 20) {
;             if (wc == 0) {
; #pragma unroll
;                 for (int ai = 0; ai < 2; ++ai)
; #pragma unroll
;                     for (int m = 0; m < 4; ++m) { const int row = row0 + ai * HALF + m * 16; const float rs = rsqrtf(ep[ai * 4 + m] * (1.0f / 1024.0f) + EPS);
;                         *(f32x4*)(dt + (size_t)row * 32 + 8 * fq) = acc[ai][0][m][0] * rs; *(f32x4*)(dt + (size_t)row * 32 + 8 * fq + 4) = acc[ai][0][m][1] * rs; }
;             }
;             return;
;         }
;         const int col0 = u.pn * BM + wc * 32 + 8 * fq;
; #pragma unroll
;         for (int ai = 0; ai < 2; ++ai)
; #pragma unroll
;             for (int m = 0; m < 4; ++m) { const int row = row0 + ai * HALF + m * 16; const float rs = rsqrtf(ep[ai * 4 + m] * (1.0f / 1024.0f) + EPS);
;                 u16* rowp = O + (size_t)row * ldc + col0;
; #pragma unroll
;                 for (int bj = 0; bj < 2; ++bj) { f32x4 v0 = acc[ai][bj][m][0] * rs, v1 = acc[ai][bj][m][1] * rs;
;                     if (ACT == 1) {
; #pragma unroll
;                         for (int j = 0; j < 4; ++j) { const float a0 = fmaxf(v0[j], 0.f), a1 = fmaxf(v1[j], 0.f); v0[j] = a0 * a0; v1[j] = a1 * a1; } }
;                     u32x4 w; w.x = pk2(v0[0], v0[1]); w.y = pk2(v0[2], v0[3]); w.z = pk2(v1[0], v1[1]); w.w = pk2(v1[2], v1[3]);
;                     *(u32x4*)(rowp + bj * HALF) = w; } }
; template <class Epi>
; __device__ __forceinline__ void gemm_phase(LAS unsigned char* lds, const Gemm g, const StaticOrder& S, const Epi& E) {
;     ...
;             PG8_BAR; PG8_WAIT_L(0); PG8_MMA(1, 0, At, B0); PG8_BAR; PG8_SCHED;
;             PG8_STAGE(PG8_SB(1, 1), b3 + hstepB, voffB);
;             PG8_WAIT_V(6); PG8_BAR; PG8_MMA(1, 1, At, B1); PG8_BAR;
	s_waitcnt lgkmcnt(0)
	s_setprio 1
	s_waitcnt lgkmcnt(0)
	v_mfma_f32_16x16x32_bf16 v[28:31], v[146:149], v[174:177], v[28:31]
	v_mfma_f32_16x16x32_bf16 v[24:27], v[158:161], v[174:177], v[24:27]
	v_mfma_f32_16x16x32_bf16 v[20:23], v[146:149], v[182:185], v[20:23]
	v_mfma_f32_16x16x32_bf16 v[16:19], v[158:161], v[182:185], v[16:19]
	v_mfma_f32_16x16x32_bf16 v[12:15], v[146:149], v[190:193], v[12:15]
	v_mfma_f32_16x16x32_bf16 v[8:11], v[158:161], v[190:193], v[8:11]
	v_mfma_f32_16x16x32_bf16 v[4:7], v[146:149], v[198:201], v[4:7]
	v_mfma_f32_16x16x32_bf16 v[0:3], v[158:161], v[198:201], v[0:3]
	v_mfma_f32_16x16x32_bf16 v[28:31], v[154:157], v[178:181], v[28:31]
	v_mfma_f32_16x16x32_bf16 v[24:27], v[162:165], v[178:181], v[24:27]
	v_mfma_f32_16x16x32_bf16 v[20:23], v[154:157], v[186:189], v[20:23]
	v_mfma_f32_16x16x32_bf16 v[16:19], v[162:165], v[186:189], v[16:19]
	v_mfma_f32_16x16x32_bf16 v[12:15], v[154:157], v[194:197], v[12:15]
	v_mfma_f32_16x16x32_bf16 v[8:11], v[162:165], v[194:197], v[8:11]
	v_mfma_f32_16x16x32_bf16 v[4:7], v[154:157], v[202:205], v[4:7]
	v_mfma_f32_16x16x32_bf16 v[0:3], v[162:165], v[202:205], v[0:3]
	s_setprio 0
	s_barrier
	s_add_u32 s22, s22, 0x40080
	s_addc_u32 s23, s23, 0
	s_add_i32 s24, s24, s27
	v_lshl_add_u64 v[146:147], s[22:23], 0, v[132:133]
	s_mov_b32 m0, s24
	s_nop 0
	global_load_lds_dwordx4 v[146:147], off
	v_lshl_add_u64 v[146:147], s[22:23], 0, v[128:129]
	s_add_i32 m0, s24, 0x2000
	s_nop 0
	global_load_lds_dwordx4 v[146:147], off
	s_waitcnt vmcnt(6)
	s_barrier
	s_setprio 1
	v_mfma_f32_16x16x32_bf16 v[92:95], v[206:209], v[174:177], v[92:95]
	v_mfma_f32_16x16x32_bf16 v[88:91], v[214:217], v[174:177], v[88:91]
	v_mfma_f32_16x16x32_bf16 v[84:87], v[206:209], v[182:185], v[84:87]
	v_mfma_f32_16x16x32_bf16 v[80:83], v[214:217], v[182:185], v[80:83]
	v_mfma_f32_16x16x32_bf16 v[72:75], v[206:209], v[190:193], v[72:75]
	v_mfma_f32_16x16x32_bf16 v[68:71], v[214:217], v[190:193], v[68:71]
	v_mfma_f32_16x16x32_bf16 v[52:55], v[206:209], v[198:201], v[52:55]
	v_mfma_f32_16x16x32_bf16 v[44:47], v[214:217], v[198:201], v[44:47]
	v_mfma_f32_16x16x32_bf16 v[92:95], v[210:213], v[178:181], v[92:95]
	v_mfma_f32_16x16x32_bf16 v[88:91], v[218:221], v[178:181], v[88:91]
	v_mfma_f32_16x16x32_bf16 v[84:87], v[210:213], v[186:189], v[84:87]
	v_mfma_f32_16x16x32_bf16 v[80:83], v[218:221], v[186:189], v[80:83]
	v_mfma_f32_16x16x32_bf16 v[72:75], v[210:213], v[194:197], v[72:75]
	v_mfma_f32_16x16x32_bf16 v[68:71], v[218:221], v[194:197], v[68:71]
	v_mfma_f32_16x16x32_bf16 v[52:55], v[210:213], v[202:205], v[52:55]
	v_mfma_f32_16x16x32_bf16 v[44:47], v[218:221], v[202:205], v[44:47]
	s_setprio 0
	s_add_i32 s47, s47, 2
	s_add_u32 s20, s20, 0x100
	s_addc_u32 s21, s21, 0
	s_add_u32 s45, s45, 0x100
	s_addc_u32 s46, s46, 0
	s_cmp_gt_u32 s47, 13
	s_barrier
	s_cbranch_scc0 .LBB0_205
	s_bfe_u32 vcc_lo, s18, 0x20003
	s_lshl_b32 vcc_lo, vcc_lo, 10
	s_add_i32 vcc_lo, vcc_lo, 0x20010
	v_lshl_add_u32 v236, v153, 2, vcc_lo
	ds_read_b32 v228, v236
	ds_read_b32 v229, v236 offset:64
	ds_read_b32 v230, v236 offset:128
	ds_read_b32 v231, v236 offset:192
	ds_read_b32 v232, v236 offset:512
	ds_read_b32 v233, v236 offset:576
	ds_read_b32 v234, v236 offset:640
	ds_read_b32 v235, v236 offset:704
	s_waitcnt lgkmcnt(0)
	v_lshl_add_u32 v162, s18, 8, v153
	v_ashrrev_i32_e32 v163, 31, v162
	v_or_b32_e32 v160, 16, v162
	v_or_b32_e32 v158, 32, v162
	v_or_b32_e32 v156, 48, v162
	v_ashrrev_i32_e32 v161, 31, v160
	v_ashrrev_i32_e32 v159, 31, v158
	v_ashrrev_i32_e32 v157, 31, v156
	v_add_u32_e32 v154, 0x80, v162
	v_add_u32_e32 v150, 0x90, v162
	v_add_u32_e32 v148, 0xa0, v162
	v_add_u32_e32 v146, 0xb0, v162
	v_ashrrev_i32_e32 v155, 31, v154
	v_ashrrev_i32_e32 v151, 31, v150
	v_ashrrev_i32_e32 v149, 31, v148
	v_ashrrev_i32_e32 v147, 31, v146
	s_cmp_lg_u32 s43, 20
	s_mov_b64 s[18:19], -1
	s_cbranch_scc0 .LBB0_208
	s_waitcnt vmcnt(8)
	v_lshl_or_b32 v166, s43, 8, v169
	v_ashrrev_i32_e32 v167, 31, v166
	v_lshlrev_b64 v[166:167], 1, v[166:167]
	v_mov_b32_e32 v186, v228
	v_mov_b64_e32 v[164:165], s[96:97]
	v_mad_i64_i32 v[182:183], s[18:19], v162, s42, v[164:165]
	v_lshl_add_u64 v[188:189], v[182:183], 0, v[166:167]
	v_pk_mul_f32 v[184:185], v[78:79], v[186:187] op_sel_hi:[1,0]
	v_pk_mul_f32 v[182:183], v[76:77], v[186:187] op_sel_hi:[1,0]
	v_pk_mul_f32 v[190:191], v[66:67], v[186:187] op_sel_hi:[1,0]
	v_pk_mul_f32 v[192:193], v[64:65], v[186:187] op_sel_hi:[1,0]
	v_cvt_pk_bf16_f32 v182, v182, v183
	v_cvt_pk_bf16_f32 v183, v184, v185
	v_cvt_pk_bf16_f32 v184, v192, v193
	v_cvt_pk_bf16_f32 v185, v190, v191
	v_pk_mul_f32 v[124:125], v[124:125], v[186:187] op_sel_hi:[1,0]
	global_store_dwordx4 v[188:189], v[182:185], off
	v_pk_mul_f32 v[126:127], v[126:127], v[186:187] op_sel_hi:[1,0]
	s_nop 0
	v_pk_mul_f32 v[182:183], v[122:123], v[186:187] op_sel_hi:[1,0]
	v_pk_mul_f32 v[122:123], v[120:121], v[186:187] op_sel_hi:[1,0]
	v_cvt_pk_bf16_f32 v120, v124, v125
	v_cvt_pk_bf16_f32 v121, v126, v127
	v_cvt_pk_bf16_f32 v122, v122, v123
	v_cvt_pk_bf16_f32 v123, v182, v183
	global_store_dwordx4 v[188:189], v[120:123], off offset:256
	s_nop 1
	v_mov_b32_e32 v124, v229
	v_mad_i64_i32 v[120:121], s[18:19], v160, s42, v[164:165]
	v_lshl_add_u64 v[126:127], v[120:121], 0, v[166:167]
	v_pk_mul_f32 v[122:123], v[62:63], v[124:125] op_sel_hi:[1,0]
	v_pk_mul_f32 v[120:121], v[60:61], v[124:125] op_sel_hi:[1,0]
	v_pk_mul_f32 v[182:183], v[58:59], v[124:125] op_sel_hi:[1,0]
	v_pk_mul_f32 v[184:185], v[56:57], v[124:125] op_sel_hi:[1,0]
	v_cvt_pk_bf16_f32 v120, v120, v121
	v_cvt_pk_bf16_f32 v121, v122, v123
	v_cvt_pk_bf16_f32 v122, v184, v185
	v_cvt_pk_bf16_f32 v123, v182, v183
; __device__ __forceinline__ unsigned pk2(float lo, float hi) { const f32x2 v = (f32x2){lo, hi}; const bf16x2_t b = __builtin_convertvector(v, bf16x2_t); return __builtin_bit_cast(unsigned, b); }
;     __device__ __forceinline__ void operator()(const f32x4 (&acc)[2][2][4][2], const Unit& u, int wr, int wc, int fr, int fq, const float (&)[8]) const {
;     ...
;             for (int m = 0; m < 4; ++m) { const int row = row0 + ai * HALF + m * 16; const float rs = rsqrtf(ep[ai * 4 + m] * (1.0f / 1024.0f) + EPS);
;                 u16* rowp = O + (size_t)row * ldc + col0;
; #pragma unroll
;                 for (int bj = 0; bj < 2; ++bj) { f32x4 v0 = acc[ai][bj][m][0] * rs, v1 = acc[ai][bj][m][1] * rs;
;                     if (ACT == 1) {
; #pragma unroll
;                         for (int j = 0; j < 4; ++j) { const float a0 = fmaxf(v0[j], 0.f), a1 = fmaxf(v1[j], 0.f); v0[j] = a0 * a0; v1[j] = a1 * a1; } }
;                     u32x4 w; w.x = pk2(v0[0], v0[1]); w.y = pk2(v0[2], v0[3]); w.z = pk2(v1[0], v1[1]); w.w = pk2(v1[2], v1[3]);
;                     *(u32x4*)(rowp + bj * HALF) = w; } }
	v_pk_mul_f32 v[116:117], v[116:117], v[124:125] op_sel_hi:[1,0]
	global_store_dwordx4 v[126:127], v[120:123], off
	v_pk_mul_f32 v[118:119], v[118:119], v[124:125] op_sel_hi:[1,0]
	s_nop 0
	v_pk_mul_f32 v[120:121], v[114:115], v[124:125] op_sel_hi:[1,0]
	v_pk_mul_f32 v[114:115], v[112:113], v[124:125] op_sel_hi:[1,0]
	v_cvt_pk_bf16_f32 v112, v116, v117
	v_cvt_pk_bf16_f32 v113, v118, v119
	v_cvt_pk_bf16_f32 v114, v114, v115
	v_cvt_pk_bf16_f32 v115, v120, v121
	global_store_dwordx4 v[126:127], v[112:115], off offset:256
	s_nop 1
	v_mov_b32_e32 v116, v230
	v_mad_i64_i32 v[112:113], s[18:19], v158, s42, v[164:165]
	v_lshl_add_u64 v[118:119], v[112:113], 0, v[166:167]
	v_pk_mul_f32 v[114:115], v[50:51], v[116:117] op_sel_hi:[1,0]
	v_pk_mul_f32 v[112:113], v[48:49], v[116:117] op_sel_hi:[1,0]
	v_pk_mul_f32 v[120:121], v[42:43], v[116:117] op_sel_hi:[1,0]
	v_pk_mul_f32 v[122:123], v[40:41], v[116:117] op_sel_hi:[1,0]
	v_cvt_pk_bf16_f32 v112, v112, v113
	v_cvt_pk_bf16_f32 v113, v114, v115
	v_cvt_pk_bf16_f32 v114, v122, v123
	v_cvt_pk_bf16_f32 v115, v120, v121
	v_pk_mul_f32 v[108:109], v[108:109], v[116:117] op_sel_hi:[1,0]
	global_store_dwordx4 v[118:119], v[112:115], off
	v_pk_mul_f32 v[110:111], v[110:111], v[116:117] op_sel_hi:[1,0]
	s_nop 0
	v_pk_mul_f32 v[112:113], v[106:107], v[116:117] op_sel_hi:[1,0]
	v_pk_mul_f32 v[106:107], v[104:105], v[116:117] op_sel_hi:[1,0]
	v_cvt_pk_bf16_f32 v104, v108, v109
	v_cvt_pk_bf16_f32 v105, v110, v111
	v_cvt_pk_bf16_f32 v106, v106, v107
	v_cvt_pk_bf16_f32 v107, v112, v113
	global_store_dwordx4 v[118:119], v[104:107], off offset:256
	s_nop 1
	v_mov_b32_e32 v108, v231
	v_mad_i64_i32 v[104:105], s[18:19], v156, s42, v[164:165]
	v_lshl_add_u64 v[110:111], v[104:105], 0, v[166:167]
	v_pk_mul_f32 v[106:107], v[38:39], v[108:109] op_sel_hi:[1,0]
	v_pk_mul_f32 v[104:105], v[36:37], v[108:109] op_sel_hi:[1,0]
	v_pk_mul_f32 v[112:113], v[34:35], v[108:109] op_sel_hi:[1,0]
	v_pk_mul_f32 v[114:115], v[32:33], v[108:109] op_sel_hi:[1,0]
	v_cvt_pk_bf16_f32 v104, v104, v105
	v_cvt_pk_bf16_f32 v105, v106, v107
	v_cvt_pk_bf16_f32 v106, v114, v115
	v_cvt_pk_bf16_f32 v107, v112, v113
	v_pk_mul_f32 v[100:101], v[100:101], v[108:109] op_sel_hi:[1,0]
	global_store_dwordx4 v[110:111], v[104:107], off
	v_pk_mul_f32 v[102:103], v[102:103], v[108:109] op_sel_hi:[1,0]
	s_nop 0
	v_pk_mul_f32 v[104:105], v[98:99], v[108:109] op_sel_hi:[1,0]
	v_pk_mul_f32 v[98:99], v[96:97], v[108:109] op_sel_hi:[1,0]
	v_cvt_pk_bf16_f32 v96, v100, v101
	v_cvt_pk_bf16_f32 v97, v102, v103
	v_cvt_pk_bf16_f32 v98, v98, v99
	v_cvt_pk_bf16_f32 v99, v104, v105
	global_store_dwordx4 v[110:111], v[96:99], off offset:256
	s_nop 1
	v_mov_b32_e32 v100, v232
	v_mad_i64_i32 v[96:97], s[18:19], v154, s42, v[164:165]
	v_lshl_add_u64 v[102:103], v[96:97], 0, v[166:167]
	v_pk_mul_f32 v[98:99], v[30:31], v[100:101] op_sel_hi:[1,0]
	v_pk_mul_f32 v[96:97], v[28:29], v[100:101] op_sel_hi:[1,0]
	v_pk_mul_f32 v[104:105], v[26:27], v[100:101] op_sel_hi:[1,0]
	v_pk_mul_f32 v[106:107], v[24:25], v[100:101] op_sel_hi:[1,0]
	v_cvt_pk_bf16_f32 v96, v96, v97
	v_cvt_pk_bf16_f32 v97, v98, v99
	v_cvt_pk_bf16_f32 v98, v106, v107
	v_cvt_pk_bf16_f32 v99, v104, v105
	v_pk_mul_f32 v[92:93], v[92:93], v[100:101] op_sel_hi:[1,0]
	global_store_dwordx4 v[102:103], v[96:99], off
	v_pk_mul_f32 v[94:95], v[94:95], v[100:101] op_sel_hi:[1,0]
	s_nop 0
	v_pk_mul_f32 v[96:97], v[90:91], v[100:101] op_sel_hi:[1,0]
	v_pk_mul_f32 v[90:91], v[88:89], v[100:101] op_sel_hi:[1,0]
	v_cvt_pk_bf16_f32 v88, v92, v93
	v_cvt_pk_bf16_f32 v89, v94, v95
	v_cvt_pk_bf16_f32 v90, v90, v91
	v_cvt_pk_bf16_f32 v91, v96, v97
	global_store_dwordx4 v[102:103], v[88:91], off offset:256
	s_nop 1
	v_mov_b32_e32 v92, v233
	v_mad_i64_i32 v[88:89], s[18:19], v150, s42, v[164:165]
	v_lshl_add_u64 v[94:95], v[88:89], 0, v[166:167]
	v_pk_mul_f32 v[90:91], v[22:23], v[92:93] op_sel_hi:[1,0]
	v_pk_mul_f32 v[88:89], v[20:21], v[92:93] op_sel_hi:[1,0]
	v_pk_mul_f32 v[96:97], v[18:19], v[92:93] op_sel_hi:[1,0]
	v_pk_mul_f32 v[98:99], v[16:17], v[92:93] op_sel_hi:[1,0]
	v_cvt_pk_bf16_f32 v88, v88, v89
	v_cvt_pk_bf16_f32 v89, v90, v91
	v_cvt_pk_bf16_f32 v90, v98, v99
	v_cvt_pk_bf16_f32 v91, v96, v97
	v_pk_mul_f32 v[84:85], v[84:85], v[92:93] op_sel_hi:[1,0]
	global_store_dwordx4 v[94:95], v[88:91], off
	v_pk_mul_f32 v[86:87], v[86:87], v[92:93] op_sel_hi:[1,0]
	s_nop 0
	v_pk_mul_f32 v[88:89], v[82:83], v[92:93] op_sel_hi:[1,0]
	v_pk_mul_f32 v[82:83], v[80:81], v[92:93] op_sel_hi:[1,0]
	v_cvt_pk_bf16_f32 v80, v84, v85
	v_cvt_pk_bf16_f32 v81, v86, v87
	v_cvt_pk_bf16_f32 v82, v82, v83
	v_cvt_pk_bf16_f32 v83, v88, v89
	global_store_dwordx4 v[94:95], v[80:83], off offset:256
	s_nop 1
	v_mov_b32_e32 v84, v234
	v_mad_i64_i32 v[80:81], s[18:19], v148, s42, v[164:165]
	v_lshl_add_u64 v[86:87], v[80:81], 0, v[166:167]
	v_pk_mul_f32 v[82:83], v[14:15], v[84:85] op_sel_hi:[1,0]
	v_pk_mul_f32 v[80:81], v[12:13], v[84:85] op_sel_hi:[1,0]
	v_pk_mul_f32 v[88:89], v[10:11], v[84:85] op_sel_hi:[1,0]
	v_pk_mul_f32 v[90:91], v[8:9], v[84:85] op_sel_hi:[1,0]
	v_cvt_pk_bf16_f32 v80, v80, v81
	v_cvt_pk_bf16_f32 v81, v82, v83
	v_cvt_pk_bf16_f32 v82, v90, v91
	v_cvt_pk_bf16_f32 v83, v88, v89
	v_pk_mul_f32 v[72:73], v[72:73], v[84:85] op_sel_hi:[1,0]
	global_store_dwordx4 v[86:87], v[80:83], off
	v_pk_mul_f32 v[74:75], v[74:75], v[84:85] op_sel_hi:[1,0]
	s_nop 0
	v_pk_mul_f32 v[80:81], v[70:71], v[84:85] op_sel_hi:[1,0]
	v_pk_mul_f32 v[70:71], v[68:69], v[84:85] op_sel_hi:[1,0]
	v_cvt_pk_bf16_f32 v68, v72, v73
	v_cvt_pk_bf16_f32 v69, v74, v75
	v_cvt_pk_bf16_f32 v70, v70, v71
	v_cvt_pk_bf16_f32 v71, v80, v81
	global_store_dwordx4 v[86:87], v[68:71], off offset:256
	s_nop 1
	v_mov_b32_e32 v72, v235
	v_mad_i64_i32 v[68:69], s[18:19], v146, s42, v[164:165]
	v_lshl_add_u64 v[74:75], v[68:69], 0, v[166:167]
	v_pk_mul_f32 v[70:71], v[6:7], v[72:73] op_sel_hi:[1,0]
	v_pk_mul_f32 v[68:69], v[4:5], v[72:73] op_sel_hi:[1,0]
	v_pk_mul_f32 v[80:81], v[2:3], v[72:73] op_sel_hi:[1,0]
	v_pk_mul_f32 v[82:83], v[0:1], v[72:73] op_sel_hi:[1,0]
	v_cvt_pk_bf16_f32 v68, v68, v69
	v_cvt_pk_bf16_f32 v69, v70, v71
	v_cvt_pk_bf16_f32 v70, v82, v83
	v_cvt_pk_bf16_f32 v71, v80, v81
	global_store_dwordx4 v[74:75], v[68:71], off
	v_pk_mul_f32 v[54:55], v[54:55], v[72:73] op_sel_hi:[1,0]
	v_pk_mul_f32 v[52:53], v[52:53], v[72:73] op_sel_hi:[1,0]
	v_pk_mul_f32 v[68:69], v[46:47], v[72:73] op_sel_hi:[1,0]
	v_pk_mul_f32 v[46:47], v[44:45], v[72:73] op_sel_hi:[1,0]
	v_cvt_pk_bf16_f32 v44, v52, v53
	v_cvt_pk_bf16_f32 v45, v54, v55
	v_cvt_pk_bf16_f32 v46, v46, v47
	v_cvt_pk_bf16_f32 v47, v68, v69
	global_store_dwordx4 v[74:75], v[44:47], off offset:256
	s_mov_b64 s[18:19], 0
;     __device__ __forceinline__ void operator()(const f32x4 (&acc)[2][2][4][2], const Unit& u, int wr, int wc, int fr, int fq, const float (&)[8]) const {
;     ...
;         if (DT && u.pn == 20) {
;             if (wc == 0) {
; #pragma unroll
;                 for (int ai = 0; ai < 2; ++ai)
; #pragma unroll
;                     for (int m = 0; m < 4; ++m) { const int row = row0 + ai * HALF + m * 16; const float rs = rsqrtf(ep[ai * 4 + m] * (1.0f / 1024.0f) + EPS);
;                         *(f32x4*)(dt + (size_t)row * 32 + 8 * fq) = acc[ai][0][m][0] * rs; *(f32x4*)(dt + (size_t)row * 32 + 8 * fq + 4) = acc[ai][0][m][1] * rs; }
;             }
;             return;
;         }
.LBB0_208:
	s_andn2_b64 vcc, exec, s[18:19]
	s_cbranch_vccnz .LBB0_201
	s_andn2_b64 vcc, exec, s[8:9]
	s_cbranch_vccnz .LBB0_201
	s_waitcnt vmcnt(8)
	v_lshlrev_b64 v[52:53], 7, v[162:163]
	v_lshl_add_u64 v[52:53], v[136:137], 0, v[52:53]
	s_nop 0
	v_mov_b32_e32 v54, v228
	v_pk_mul_f32 v[46:47], v[78:79], v[54:55] op_sel_hi:[1,0]
	v_pk_mul_f32 v[44:45], v[76:77], v[54:55] op_sel_hi:[1,0]
	global_store_dwordx4 v[52:53], v[44:47], off
	s_nop 1
	s_nop 1
	s_nop 0
	v_pk_mul_f32 v[46:47], v[66:67], v[54:55] op_sel_hi:[1,0]
	v_pk_mul_f32 v[44:45], v[64:65], v[54:55] op_sel_hi:[1,0]
	global_store_dwordx4 v[52:53], v[44:47], off offset:16
	s_nop 1
	v_mov_b32_e32 v52, v229
	v_lshlrev_b64 v[54:55], 7, v[160:161]
	v_pk_mul_f32 v[46:47], v[62:63], v[52:53] op_sel_hi:[1,0]
	v_pk_mul_f32 v[44:45], v[60:61], v[52:53] op_sel_hi:[1,0]
	v_lshl_add_u64 v[54:55], v[136:137], 0, v[54:55]
	global_store_dwordx4 v[54:55], v[44:47], off
	s_nop 1
	s_nop 1
	s_nop 0
	v_pk_mul_f32 v[46:47], v[58:59], v[52:53] op_sel_hi:[1,0]
	v_pk_mul_f32 v[44:45], v[56:57], v[52:53] op_sel_hi:[1,0]
	global_store_dwordx4 v[54:55], v[44:47], off offset:16
	s_nop 1
	v_mov_b32_e32 v52, v230
	v_pk_mul_f32 v[44:45], v[48:49], v[52:53] op_sel_hi:[1,0]
	v_lshlrev_b64 v[48:49], 7, v[158:159]
	v_pk_mul_f32 v[46:47], v[50:51], v[52:53] op_sel_hi:[1,0]
	v_lshl_add_u64 v[48:49], v[136:137], 0, v[48:49]
	global_store_dwordx4 v[48:49], v[44:47], off
	v_pk_mul_f32 v[42:43], v[42:43], v[52:53] op_sel_hi:[1,0]
	v_pk_mul_f32 v[40:41], v[40:41], v[52:53] op_sel_hi:[1,0]
	global_store_dwordx4 v[48:49], v[40:43], off offset:16
	s_nop 0
	s_nop 0
	v_lshlrev_b64 v[42:43], 7, v[156:157]
	v_lshl_add_u64 v[42:43], v[136:137], 0, v[42:43]
	v_mov_b32_e32 v40, v231
	v_pk_mul_f32 v[38:39], v[38:39], v[40:41] op_sel_hi:[1,0]
	v_pk_mul_f32 v[36:37], v[36:37], v[40:41] op_sel_hi:[1,0]
	global_store_dwordx4 v[42:43], v[36:39], off
	v_pk_mul_f32 v[34:35], v[34:35], v[40:41] op_sel_hi:[1,0]
	v_pk_mul_f32 v[32:33], v[32:33], v[40:41] op_sel_hi:[1,0]
	global_store_dwordx4 v[42:43], v[32:35], off offset:16
	s_nop 0
	s_nop 0
	v_lshlrev_b64 v[34:35], 7, v[154:155]
	v_lshl_add_u64 v[34:35], v[136:137], 0, v[34:35]
	v_mov_b32_e32 v32, v232
	v_pk_mul_f32 v[30:31], v[30:31], v[32:33] op_sel_hi:[1,0]
	v_pk_mul_f32 v[28:29], v[28:29], v[32:33] op_sel_hi:[1,0]
	global_store_dwordx4 v[34:35], v[28:31], off
	v_pk_mul_f32 v[26:27], v[26:27], v[32:33] op_sel_hi:[1,0]
	v_pk_mul_f32 v[24:25], v[24:25], v[32:33] op_sel_hi:[1,0]
	global_store_dwordx4 v[34:35], v[24:27], off offset:16
	s_nop 0
	s_nop 0
	v_lshlrev_b64 v[26:27], 7, v[150:151]
	v_lshl_add_u64 v[26:27], v[136:137], 0, v[26:27]
	v_mov_b32_e32 v24, v233
	v_pk_mul_f32 v[22:23], v[22:23], v[24:25] op_sel_hi:[1,0]
	v_pk_mul_f32 v[20:21], v[20:21], v[24:25] op_sel_hi:[1,0]
	global_store_dwordx4 v[26:27], v[20:23], off
	v_pk_mul_f32 v[18:19], v[18:19], v[24:25] op_sel_hi:[1,0]
	v_pk_mul_f32 v[16:17], v[16:17], v[24:25] op_sel_hi:[1,0]
	global_store_dwordx4 v[26:27], v[16:19], off offset:16
	s_nop 0
	s_nop 0
	v_lshlrev_b64 v[18:19], 7, v[148:149]
	v_lshl_add_u64 v[18:19], v[136:137], 0, v[18:19]
	v_mov_b32_e32 v16, v234
	v_pk_mul_f32 v[14:15], v[14:15], v[16:17] op_sel_hi:[1,0]
	v_pk_mul_f32 v[12:13], v[12:13], v[16:17] op_sel_hi:[1,0]
	global_store_dwordx4 v[18:19], v[12:15], off
	v_pk_mul_f32 v[10:11], v[10:11], v[16:17] op_sel_hi:[1,0]
	v_pk_mul_f32 v[8:9], v[8:9], v[16:17] op_sel_hi:[1,0]
	global_store_dwordx4 v[18:19], v[8:11], off offset:16
	s_nop 0
	s_nop 0
	v_lshlrev_b64 v[10:11], 7, v[146:147]
	v_lshl_add_u64 v[10:11], v[136:137], 0, v[10:11]
	v_mov_b32_e32 v8, v235
	v_pk_mul_f32 v[6:7], v[6:7], v[8:9] op_sel_hi:[1,0]
	v_pk_mul_f32 v[4:5], v[4:5], v[8:9] op_sel_hi:[1,0]
	v_pk_mul_f32 v[2:3], v[2:3], v[8:9] op_sel_hi:[1,0]
	v_pk_mul_f32 v[0:1], v[0:1], v[8:9] op_sel_hi:[1,0]
	global_store_dwordx4 v[10:11], v[4:7], off
	global_store_dwordx4 v[10:11], v[0:3], off offset:16
	s_branch .LBB0_201

;     __device__ __forceinline__ void operator()(const f32x4 (&acc)[2][2][4][2], const Unit& u, int wr, int wc, int fr, int fq, const float (&)[8]) const {
;     ...
;                 else { const f32x4 pq = *(const f32x4*)(ss + (size_t)row * 16 + 4 * fq); ep[ai * 4 + m] = (pq[0] + pq[1]) + (pq[2] + pq[3]); } }
; template <class Epi>
; __device__ __forceinline__ void gemm_phase(LAS unsigned char* lds, const Gemm g, const StaticOrder& S, const Epi& E) {
;     const int tid = threadIdx.x, wid = __builtin_amdgcn_readfirstlane(tid >> 6), lane = tid & 63, wr = wid >> 2, wc = wid & 3, fr = lane & 15, fq = lane >> 4;
;     const int K = g.K, nt = K / BK, lda = g.lda;
;     unsigned voffA[2], voffB[2];
; #pragma unroll
;     for (int i = 0; i < 2; ++i) { int R, C; stage_rc(tid * 16 + i * 8192, R, C); const int Rb = Epi::PERM ? ((R & ~31) + perm32(R & 31)) : R;
;         voffA[i] = (unsigned)(R * lda + C) * 2u; voffB[i] = (unsigned)(Rb * K + C) * 2u; }
;     const size_t kstep = (size_t)(BK * 2);
;     const size_t hstepA = (size_t)HALF * lda * 2, hstepB = (size_t)HALF * K * 2;
;     const size_t tstepA = 2 * hstepA, tstepB = 2 * hstepB;
;     const unsigned ldsw = (unsigned)wid * 1024u;
;     const int aoff = lds_byte(wr * 64 + fr, fq * 8), boff = lds_byte(wc * 32 + fr, fq * 8);
;     ...
;     Unit cur, nxt; int ui = 0;
;     if (!S.next(0, cur)) return;
;     ...
;     for (int q_ = 0; q_ < ((S.c >> 3) & 3); ++q_) __builtin_amdgcn_s_sleep(100);
;     ...
;     f32x4 acc[2][2][4][2];
; #pragma unroll
;     for (int a = 0; a < 2; ++a)
; #pragma unroll
;         for (int b = 0; b < 2; ++b)
; #pragma unroll
;             for (int m = 0; m < 4; ++m)
; #pragma unroll
;                 for (int n = 0; n < 2; ++n) acc[a][b][m][n] = (f32x4){0.f, 0.f, 0.f, 0.f};
;     bf16x8 At[4][2], B0[2][2], B1[2][2]; float epre[8];
; #pragma unroll
;     for (int q_ = 0; q_ < 8; ++q_) epre[q_] = 0.f;
;     const char* cA = (const char*)g.A + (size_t)cur.pm * tstepA; const char* cB = (const char*)g.Bt + (size_t)cur.pn * tstepB;
;     PG8_STAGE(PG8_SB(0, 0), cB, voffB); PG8_STAGE(PG8_SA(0, 0), cA, voffA); PG8_STAGE(PG8_SB(0, 1), cB + hstepB, voffB); PG8_STAGE(PG8_SA(0, 1), cA + hstepA, voffA);
;     if (wr == 1) PG8_BAR;
;     PG8_WAIT_V(4); PG8_BAR;
;     PG8_STAGE(PG8_SB(1, 0), cB + kstep, voffB); PG8_STAGE(PG8_SA(1, 0), cA + kstep, voffA); PG8_STAGE(PG8_SB(1, 1), cB + hstepB + kstep, voffB);
;     PG8_WAIT_V(6); PG8_BAR;
.LBB0_914:
	s_cmp_lt_i32 s40, 9
	s_cselect_b64 s[2:3], -1, 0
	s_and_b64 s[0:1], s[2:3], s[0:1]
	s_andn2_b64 vcc, exec, s[0:1]
	s_cbranch_vccnz .LBB0_927
	s_and_b32 s50, s93, 7
	s_lshl_b32 s50, s50, 5
	s_bfe_u32 s47, s93, 0x30003
	s_add_i32 s50, s50, s47
	s_add_u32 s48, s74, 0x3c7c4000
	s_addc_u32 s49, s75, 0
	s_mov_b32 s46, 0x800000
	v_lshrrev_b32_e32 v195, 8, v152
	v_and_b32_e32 v194, 0xff, v152
	v_lshl_add_u32 v193, v195, 3, s50
	v_lshl_or_b32 v192, v193, 8, v194
	v_add_u32_e32 v191, 0x1000, v192
	v_lshlrev_b32_e32 v190, 2, v152
	v_add_u32_e32 v190, 0x20010, v190
	v_lshlrev_b32_e32 v192, 6, v192
	v_lshlrev_b32_e32 v191, 6, v191
	v_mov_b32_e32 v189, 0x358637bd
	global_load_dwordx4 v[224:227], v192, s[48:49]
	global_load_dwordx4 v[220:223], v192, s[48:49] offset:16
	global_load_dwordx4 v[216:219], v192, s[48:49] offset:32
	global_load_dwordx4 v[212:215], v192, s[48:49] offset:48
	global_load_dwordx4 v[208:211], v191, s[48:49]
	global_load_dwordx4 v[204:207], v191, s[48:49] offset:16
	global_load_dwordx4 v[200:203], v191, s[48:49] offset:32
	global_load_dwordx4 v[196:199], v191, s[48:49] offset:48
	s_waitcnt vmcnt(0)
	v_add_f32_e32 v224, v224, v225
	v_add_f32_e32 v226, v226, v227
	v_add_f32_e32 v224, v224, v226
	v_add_f32_e32 v220, v220, v221
	v_add_f32_e32 v222, v222, v223
	v_add_f32_e32 v220, v220, v222
	v_add_f32_e32 v216, v216, v217
	v_add_f32_e32 v218, v218, v219
	v_add_f32_e32 v216, v216, v218
	v_add_f32_e32 v212, v212, v213
	v_add_f32_e32 v214, v214, v215
	v_add_f32_e32 v212, v212, v214
	v_add_f32_e32 v224, v224, v220
	v_add_f32_e32 v216, v216, v212
	v_add_f32_e32 v224, v224, v216
	v_fmamk_f32 v224, v224, 0x3a800000, v189
	v_mul_f32_e32 v188, 0x4b800000, v224
	v_cmp_gt_f32_e32 vcc, s46, v224
	s_nop 1
	v_cndmask_b32_e32 v187, v224, v188, vcc
	v_rsq_f32_e32 v186, v187
	s_nop 0
	v_mul_f32_e32 v185, 0x45800000, v186
	v_cndmask_b32_e32 v185, v186, v185, vcc
	ds_write_b32 v190, v185
	v_add_f32_e32 v208, v208, v209
	v_add_f32_e32 v210, v210, v211
	v_add_f32_e32 v208, v208, v210
	v_add_f32_e32 v204, v204, v205
	v_add_f32_e32 v206, v206, v207
	v_add_f32_e32 v204, v204, v206
	v_add_f32_e32 v200, v200, v201
	v_add_f32_e32 v202, v202, v203
	v_add_f32_e32 v200, v200, v202
	v_add_f32_e32 v196, v196, v197
	v_add_f32_e32 v198, v198, v199
	v_add_f32_e32 v196, v196, v198
	v_add_f32_e32 v208, v208, v204
	v_add_f32_e32 v200, v200, v196
	v_add_f32_e32 v208, v208, v200
	v_fmamk_f32 v208, v208, 0x3a800000, v189
	v_mul_f32_e32 v188, 0x4b800000, v208
	v_cmp_gt_f32_e32 vcc, s46, v208
	s_nop 1
	v_cndmask_b32_e32 v187, v208, v188, vcc
	v_rsq_f32_e32 v186, v187
	s_nop 0
	v_mul_f32_e32 v185, 0x45800000, v186
	v_cndmask_b32_e32 v185, v186, v185, vcc
	ds_write_b32 v190, v185 offset:2048
	s_waitcnt lgkmcnt(0)
	s_barrier
	s_cmpk_gt_i32 s93, 0x13ff
	v_readfirstlane_b32 s7, v152
	s_cbranch_scc1 .LBB0_927
	s_waitcnt vmcnt(0)
	v_lshrrev_b32_e32 v0, 5, v152
	v_lshrrev_b32_e32 v2, 1, v152
	v_and_b32_e32 v0, 4, v0
	s_waitcnt lgkmcnt(0)
	v_bfe_u32 v1, v152, 2, 2
	v_and_b32_e32 v2, 24, v2
	v_or3_b32 v0, v0, v1, v2
	v_lshlrev_b32_e32 v1, 4, v152
	v_add_u32_e32 v8, 0x2000, v1
	v_lshrrev_b32_e32 v2, 7, v8
	s_movk_i32 s0, 0xe0
	v_and_b32_e32 v4, 32, v152
	v_and_or_b32 v3, v2, s0, v0
	v_bitop3_b32 v9, v1, v4, 48 bitop3:0x6c
	v_and_b32_e32 v10, 64, v152
	v_bfe_u32 v11, v152, 2, 4
	s_movk_i32 s0, 0xf0
	v_or_b32_e32 v1, v9, v10
	v_and_or_b32 v2, v2, s0, v11
	s_add_u32 s9, s74, 0x2e80000
	v_lshl_or_b32 v130, v2, 11, v1
	v_lshrrev_b32_e32 v2, 3, v152
	s_movk_i32 s0, 0x60
	s_addc_u32 s26, s75, 0
	v_and_or_b32 v0, v2, s0, v0
	s_movk_i32 s0, 0x70
	s_ashr_i32 s28, s93, 31
	v_lshl_or_b32 v132, v0, 11, v1
	v_and_or_b32 v0, v2, s0, v11
	s_lshr_b32 s0, s28, 29
	s_add_i32 s0, s93, s0
	s_lshr_b32 s4, s7, 6
	s_ashr_i32 s5, s0, 3
	s_and_b32 s0, s0, -8
	s_lshr_b32 s1, s7, 8
	s_lshl_b32 s27, s4, 10
	s_sub_i32 s0, s93, s0
	s_cmp_lt_i32 s0, 0
	s_movk_i32 s29, 0x281
	s_cselect_b32 s6, s29, 0x280
	s_mul_i32 s0, s0, s6
	s_add_i32 s0, s0, s5
	s_mul_hi_i32 s5, s0, 0x66666667
	s_lshr_b32 s6, s5, 31
	s_ashr_i32 s5, s5, 6
	s_add_i32 s5, s5, s6
	s_lshl_b32 s6, s5, 3
	s_mulk_i32 s5, 0xa0
	s_sub_i32 s5, s0, s5
	s_sext_i32_i16 s0, s5
	s_bfe_u32 s0, s0, 0x3001c
	s_add_i32 s8, s5, s0
	s_sext_i32_i16 s0, s8
	s_and_b32 s8, s8, 0xfff8
	s_sub_i32 s5, s5, s8
	s_sext_i32_i16 s5, s5
	s_lshr_b32 s0, s0, 3
	s_add_i32 s18, s6, s5
	s_ashr_i32 s19, s18, 31
	s_bfe_i64 s[12:13], s[0:1], 0x100000
	s_lshl_b64 s[10:11], s[18:19], 19
	s_lshl_b64 s[12:13], s[12:13], 19
	s_add_u32 s22, s9, s12
	s_addc_u32 s23, s26, s13
	s_add_i32 s19, s27, 0
	s_add_i32 m0, s19, 0x10000
	v_lshl_or_b32 v128, v3, 11, v1
	global_load_lds_dwordx4 v132, s[22:23]
	s_add_i32 m0, s19, 0x12000
	s_add_u32 s20, s76, s10
	v_lshl_or_b32 v134, v0, 11, v1
	global_load_lds_dwordx4 v128, s[22:23]
	s_addc_u32 s21, s77, s11
	s_mov_b32 m0, s19
	s_add_i32 s30, s19, 0x2000
	global_load_lds_dwordx4 v134, s[20:21]
	s_mov_b32 m0, s30
	s_add_u32 s10, s22, 0x40000
	global_load_lds_dwordx4 v130, s[20:21]
	s_addc_u32 s11, s23, 0
	s_add_i32 m0, s19, 0x14000
	v_mov_b32_e32 v133, 0
	global_load_lds_dwordx4 v132, s[10:11]
	s_add_i32 m0, s19, 0x16000
	v_mov_b32_e32 v129, v133
	global_load_lds_dwordx4 v128, s[10:11]
	s_add_u32 s10, s20, 0x40000
	s_addc_u32 s11, s21, 0
	s_add_i32 s31, s19, 0x4000
	s_mov_b32 m0, s31
	s_add_i32 s33, s19, 0x6000
	global_load_lds_dwordx4 v134, s[10:11]
	s_mov_b32 m0, s33
	v_mov_b32_e32 v135, v133
	global_load_lds_dwordx4 v130, s[10:11]
	v_mov_b32_e32 v131, v133
	s_mov_b32 s34, 0
	v_lshl_add_u64 v[6:7], s[22:23], 0, v[132:133]
	v_lshl_add_u64 v[4:5], s[22:23], 0, v[128:129]
	v_lshl_add_u64 v[2:3], s[20:21], 0, v[134:135]
	s_cmp_lg_u32 s1, 1
	v_lshl_add_u64 v[0:1], s[20:21], 0, v[130:131]
	s_cbranch_scc1 .LBB0_918
	s_barrier

; #define PG8_STAGE(bufoff, gbase, voff) do { _Pragma("unroll") for (int _i = 0; _i < 2; ++_i) \
;         __builtin_amdgcn_global_load_lds((const unsigned*)((const char*)(gbase) + (voff)[_i]), (LAS unsigned*)(lds + (bufoff) + ldsw + _i * 8192), 16, 0, 0); } while (0)
; #define PG8_LDA(dst, b, h) do { _Pragma("unroll") for (int m = 0; m < 4; ++m) _Pragma("unroll") for (int k = 0; k < 2; ++k) dst[m][k] = *(const LAS bf16x8*)(lds + PG8_SA(b, h) + aoff + m * 2048 + k * 1024); } while (0)
; #define PG8_LDB(dst, b, h) do { _Pragma("unroll") for (int n = 0; n < 2; ++n) _Pragma("unroll") for (int k = 0; k < 2; ++k) dst[n][k] = *(const LAS bf16x8*)(lds + PG8_SB(b, h) + boff + n * 2048 + k * 1024); } while (0)
; #define PG8_MMA(ai, bj, At, Bt) do { __builtin_amdgcn_s_setprio(1); _Pragma("unroll") for (int m = 0; m < 4; ++m) _Pragma("unroll") for (int n = 0; n < 2; ++n) _Pragma("unroll") for (int k = 0; k < 2; ++k) \
;         acc[ai][bj][m][n] = __builtin_amdgcn_mfma_f32_16x16x32_bf16(Bt[n][k], At[m][k], acc[ai][bj][m][n], 0, 0, 0); __builtin_amdgcn_s_setprio(0); } while (0)
; #define PG8_WAIT_L(n) asm volatile("s_waitcnt lgkmcnt(" #n ")" ::: "memory")
; #define PG8_BAR __builtin_amdgcn_s_barrier()
; #define PG8_SCHED __builtin_amdgcn_sched_barrier(0)
; template <class Epi>
; __device__ __forceinline__ void gemm_phase(LAS unsigned char* lds, const Gemm g, const StaticOrder& S, const Epi& E) {
;     ...
;             PG8_LDB(B0, 0, 0); PG8_SCHED; PG8_LDA(At, 0, 0); PG8_STAGE(PG8_SA(1, 1), a1 + hstepA, voffA);
;             PG8_WAIT_L(8); PG8_BAR; PG8_WAIT_L(0); PG8_MMA(0, 0, At, B0); PG8_BAR; PG8_SCHED;
;             PG8_LDB(B1, 0, 1); PG8_STAGE(PG8_SB(0, 0), b2, voffB);
;             PG8_BAR; PG8_WAIT_L(0); PG8_MMA(0, 1, At, B1); PG8_BAR;
;             PG8_LDA(At, 0, 1); PG8_STAGE(PG8_SA(0, 0), a2, voffA);
;             PG8_BAR; PG8_WAIT_L(0); PG8_MMA(1, 0, At, B0); PG8_BAR; PG8_SCHED;
.LBB0_922:
	ds_read_b128 v[146:149], v173
	ds_read_b128 v[154:157], v173 offset:1024
	ds_read_b128 v[158:161], v173 offset:2048
	ds_read_b128 v[162:165], v173 offset:3072
	s_add_u32 s22, s20, 0xfffc0080
	s_addc_u32 s23, s21, -1
	s_cmp_eq_u32 s47, 12
	s_cselect_b32 s25, s13, s23
	s_cselect_b32 s24, s43, s22
	s_cselect_b32 s23, s11, s46
	s_cselect_b32 s22, s44, s45
	v_lshl_add_u64 v[150:151], s[20:21], 0, v[138:139]
	s_add_i32 m0, s19, 0xc000
	ds_read_b128 v[166:169], v174
	ds_read_b128 v[178:181], v174 offset:1024
	ds_read_b128 v[182:185], v174 offset:2048
	ds_read_b128 v[186:189], v174 offset:3072
	ds_read_b128 v[190:193], v174 offset:4096
	ds_read_b128 v[194:197], v174 offset:5120
	ds_read_b128 v[198:201], v174 offset:6144
	ds_read_b128 v[202:205], v174 offset:7168
	global_load_lds_dwordx4 v[150:151], off
	v_lshl_add_u64 v[150:151], s[20:21], 0, v[140:141]
	s_add_i32 m0, s19, 0xe000
	s_nop 0
	global_load_lds_dwordx4 v[150:151], off
	s_waitcnt lgkmcnt(8)
	s_barrier
	s_waitcnt lgkmcnt(0)
	s_setprio 1
	s_waitcnt lgkmcnt(0)
	v_mfma_f32_16x16x32_bf16 v[124:127], v[146:149], v[166:169], v[124:127]
	v_mfma_f32_16x16x32_bf16 v[120:123], v[158:161], v[166:169], v[120:123]
	v_mfma_f32_16x16x32_bf16 v[112:115], v[146:149], v[182:185], v[112:115]
	v_mfma_f32_16x16x32_bf16 v[104:107], v[158:161], v[182:185], v[104:107]
	v_mfma_f32_16x16x32_bf16 v[92:95], v[146:149], v[190:193], v[92:95]
	v_mfma_f32_16x16x32_bf16 v[88:91], v[158:161], v[190:193], v[88:91]
	v_mfma_f32_16x16x32_bf16 v[80:83], v[146:149], v[198:201], v[80:83]
	v_mfma_f32_16x16x32_bf16 v[72:75], v[158:161], v[198:201], v[72:75]
	v_mfma_f32_16x16x32_bf16 v[124:127], v[154:157], v[178:181], v[124:127]
	v_mfma_f32_16x16x32_bf16 v[120:123], v[162:165], v[178:181], v[120:123]
	v_mfma_f32_16x16x32_bf16 v[112:115], v[154:157], v[186:189], v[112:115]
	v_mfma_f32_16x16x32_bf16 v[104:107], v[162:165], v[186:189], v[104:107]
	v_mfma_f32_16x16x32_bf16 v[92:95], v[154:157], v[194:197], v[92:95]
	v_mfma_f32_16x16x32_bf16 v[88:91], v[162:165], v[194:197], v[88:91]
	v_mfma_f32_16x16x32_bf16 v[80:83], v[154:157], v[202:205], v[80:83]
	v_mfma_f32_16x16x32_bf16 v[72:75], v[162:165], v[202:205], v[72:75]
	s_setprio 0
	s_barrier
	s_add_i32 s48, s38, s27
	v_lshl_add_u64 v[150:151], s[22:23], 0, v[132:133]
	s_mov_b32 m0, s48
	ds_read_b128 v[206:209], v175
	ds_read_b128 v[210:213], v175 offset:1024
	ds_read_b128 v[214:217], v175 offset:2048
	ds_read_b128 v[218:221], v175 offset:3072
	global_load_lds_dwordx4 v[150:151], off
	v_lshl_add_u64 v[222:223], s[22:23], 0, v[128:129]
	s_add_i32 m0, s48, 0x2000
	s_nop 0
	global_load_lds_dwordx4 v[222:223], off
	s_barrier
	s_waitcnt lgkmcnt(0)
	s_setprio 1
	s_waitcnt lgkmcnt(0)
	v_mfma_f32_16x16x32_bf16 v[116:119], v[206:209], v[166:169], v[116:119]
	v_mfma_f32_16x16x32_bf16 v[108:111], v[214:217], v[166:169], v[108:111]
	v_mfma_f32_16x16x32_bf16 v[100:103], v[206:209], v[182:185], v[100:103]
	v_mfma_f32_16x16x32_bf16 v[96:99], v[214:217], v[182:185], v[96:99]
	v_mfma_f32_16x16x32_bf16 v[84:87], v[206:209], v[190:193], v[84:87]
	v_mfma_f32_16x16x32_bf16 v[76:79], v[214:217], v[190:193], v[76:79]
	v_mfma_f32_16x16x32_bf16 v[68:71], v[206:209], v[198:201], v[68:71]
	v_mfma_f32_16x16x32_bf16 v[64:67], v[214:217], v[198:201], v[64:67]
	v_mfma_f32_16x16x32_bf16 v[116:119], v[210:213], v[178:181], v[116:119]
	v_mfma_f32_16x16x32_bf16 v[108:111], v[218:221], v[178:181], v[108:111]
	v_mfma_f32_16x16x32_bf16 v[100:103], v[210:213], v[186:189], v[100:103]
	v_mfma_f32_16x16x32_bf16 v[96:99], v[218:221], v[186:189], v[96:99]
	v_mfma_f32_16x16x32_bf16 v[84:87], v[210:213], v[194:197], v[84:87]
	v_mfma_f32_16x16x32_bf16 v[76:79], v[218:221], v[194:197], v[76:79]
	v_mfma_f32_16x16x32_bf16 v[68:71], v[210:213], v[202:205], v[68:71]
	v_mfma_f32_16x16x32_bf16 v[64:67], v[218:221], v[202:205], v[64:67]
	s_setprio 0
	s_mov_b32 m0, s19
	v_lshl_add_u64 v[224:225], s[24:25], 0, v[134:135]
	s_barrier
	ds_read_b128 v[166:169], v174 offset:16384
	ds_read_b128 v[178:181], v174 offset:17408
	ds_read_b128 v[182:185], v174 offset:18432
	ds_read_b128 v[186:189], v174 offset:19456
	ds_read_b128 v[190:193], v174 offset:20480
	ds_read_b128 v[194:197], v174 offset:21504
	ds_read_b128 v[198:201], v174 offset:22528
	ds_read_b128 v[202:205], v174 offset:23552
	global_load_lds_dwordx4 v[224:225], off
	v_lshl_add_u64 v[226:227], s[24:25], 0, v[130:131]
	s_mov_b32 m0, s30
	s_nop 0
	global_load_lds_dwordx4 v[226:227], off
	s_barrier
	s_waitcnt lgkmcnt(0)
	s_setprio 1
	s_waitcnt lgkmcnt(0)
	v_mfma_f32_16x16x32_bf16 v[60:63], v[146:149], v[166:169], v[60:63]
	v_mfma_f32_16x16x32_bf16 v[56:59], v[158:161], v[166:169], v[56:59]
	v_mfma_f32_16x16x32_bf16 v[48:51], v[146:149], v[182:185], v[48:51]
	v_mfma_f32_16x16x32_bf16 v[40:43], v[158:161], v[182:185], v[40:43]
	v_mfma_f32_16x16x32_bf16 v[32:35], v[146:149], v[190:193], v[32:35]
	v_mfma_f32_16x16x32_bf16 v[24:27], v[158:161], v[190:193], v[24:27]
	v_mfma_f32_16x16x32_bf16 v[16:19], v[146:149], v[198:201], v[16:19]
	v_mfma_f32_16x16x32_bf16 v[8:11], v[158:161], v[198:201], v[8:11]
	v_mfma_f32_16x16x32_bf16 v[60:63], v[154:157], v[178:181], v[60:63]
	v_mfma_f32_16x16x32_bf16 v[56:59], v[162:165], v[178:181], v[56:59]
	v_mfma_f32_16x16x32_bf16 v[48:51], v[154:157], v[186:189], v[48:51]
	v_mfma_f32_16x16x32_bf16 v[40:43], v[162:165], v[186:189], v[40:43]
	v_mfma_f32_16x16x32_bf16 v[32:35], v[154:157], v[194:197], v[32:35]
	v_mfma_f32_16x16x32_bf16 v[24:27], v[162:165], v[194:197], v[24:27]
	v_mfma_f32_16x16x32_bf16 v[16:19], v[154:157], v[202:205], v[16:19]
	v_mfma_f32_16x16x32_bf16 v[8:11], v[162:165], v[202:205], v[8:11]
	s_setprio 0
	s_barrier
; #define PG8_STAGE(bufoff, gbase, voff) do { _Pragma("unroll") for (int _i = 0; _i < 2; ++_i) \
;         __builtin_amdgcn_global_load_lds((const unsigned*)((const char*)(gbase) + (voff)[_i]), (LAS unsigned*)(lds + (bufoff) + ldsw + _i * 8192), 16, 0, 0); } while (0)
; #define PG8_LDA(dst, b, h) do { _Pragma("unroll") for (int m = 0; m < 4; ++m) _Pragma("unroll") for (int k = 0; k < 2; ++k) dst[m][k] = *(const LAS bf16x8*)(lds + PG8_SA(b, h) + aoff + m * 2048 + k * 1024); } while (0)
; #define PG8_LDB(dst, b, h) do { _Pragma("unroll") for (int n = 0; n < 2; ++n) _Pragma("unroll") for (int k = 0; k < 2; ++k) dst[n][k] = *(const LAS bf16x8*)(lds + PG8_SB(b, h) + boff + n * 2048 + k * 1024); } while (0)
; #define PG8_MMA(ai, bj, At, Bt) do { __builtin_amdgcn_s_setprio(1); _Pragma("unroll") for (int m = 0; m < 4; ++m) _Pragma("unroll") for (int n = 0; n < 2; ++n) _Pragma("unroll") for (int k = 0; k < 2; ++k) \
;         acc[ai][bj][m][n] = __builtin_amdgcn_mfma_f32_16x16x32_bf16(Bt[n][k], At[m][k], acc[ai][bj][m][n], 0, 0, 0); __builtin_amdgcn_s_setprio(0); } while (0)
; #define PG8_WAIT_V(n) asm volatile("s_waitcnt vmcnt(" #n ")" ::: "memory")
; #define PG8_WAIT_L(n) asm volatile("s_waitcnt lgkmcnt(" #n ")" ::: "memory")
; #define PG8_BAR __builtin_amdgcn_s_barrier()
; #define PG8_SCHED __builtin_amdgcn_sched_barrier(0)
; template <class Epi>
; __device__ __forceinline__ void gemm_phase(LAS unsigned char* lds, const Gemm g, const StaticOrder& S, const Epi& E) {
;     ...
;             PG8_STAGE(PG8_SB(0, 1), b2 + hstepB, voffB);
;             PG8_WAIT_V(6); PG8_BAR; PG8_MMA(1, 1, At, B1); PG8_BAR;
;             PG8_LDB(B0, 1, 0); PG8_SCHED; PG8_LDA(At, 1, 0); PG8_STAGE(PG8_SA(0, 1), a2 + hstepA, voffA);
;             PG8_WAIT_L(8); PG8_BAR; PG8_WAIT_L(0); PG8_MMA(0, 0, At, B0); PG8_BAR; PG8_SCHED;
;             PG8_LDB(B1, 1, 1); PG8_STAGE(PG8_SB(1, 0), b3, voffB);
;             PG8_BAR; PG8_WAIT_L(0); PG8_MMA(0, 1, At, B1); PG8_BAR;
;             PG8_LDA(At, 1, 1); PG8_STAGE(PG8_SA(1, 0), a3, voffA);
	s_add_u32 s48, s22, 0x40000
	s_addc_u32 s49, s23, 0
	s_add_i32 s50, s39, s27
	v_lshl_add_u64 v[146:147], s[48:49], 0, v[132:133]
	s_mov_b32 m0, s50
	s_nop 0
	global_load_lds_dwordx4 v[146:147], off
	v_lshl_add_u64 v[146:147], s[48:49], 0, v[128:129]
	s_add_i32 m0, s50, 0x2000
	s_nop 0
	global_load_lds_dwordx4 v[146:147], off
	s_waitcnt vmcnt(6)
	s_barrier
	s_setprio 1
	v_mfma_f32_16x16x32_bf16 v[52:55], v[206:209], v[166:169], v[52:55]
	v_mfma_f32_16x16x32_bf16 v[44:47], v[214:217], v[166:169], v[44:47]
	v_mfma_f32_16x16x32_bf16 v[36:39], v[206:209], v[182:185], v[36:39]
	v_mfma_f32_16x16x32_bf16 v[28:31], v[214:217], v[182:185], v[28:31]
	v_mfma_f32_16x16x32_bf16 v[20:23], v[206:209], v[190:193], v[20:23]
	v_mfma_f32_16x16x32_bf16 v[12:15], v[214:217], v[190:193], v[12:15]
	v_mfma_f32_16x16x32_bf16 v[4:7], v[206:209], v[198:201], v[4:7]
	v_mfma_f32_16x16x32_bf16 v[0:3], v[214:217], v[198:201], v[0:3]
	v_mfma_f32_16x16x32_bf16 v[52:55], v[210:213], v[178:181], v[52:55]
	v_mfma_f32_16x16x32_bf16 v[44:47], v[218:221], v[178:181], v[44:47]
	v_mfma_f32_16x16x32_bf16 v[36:39], v[210:213], v[186:189], v[36:39]
	v_mfma_f32_16x16x32_bf16 v[28:31], v[218:221], v[186:189], v[28:31]
	v_mfma_f32_16x16x32_bf16 v[20:23], v[210:213], v[194:197], v[20:23]
	v_mfma_f32_16x16x32_bf16 v[12:15], v[218:221], v[194:197], v[12:15]
	v_mfma_f32_16x16x32_bf16 v[4:7], v[210:213], v[202:205], v[4:7]
	v_mfma_f32_16x16x32_bf16 v[0:3], v[218:221], v[202:205], v[0:3]
	s_setprio 0
	s_add_i32 s48, 0, 0x18000
	v_add_u32_e32 v162, s48, v171
	s_barrier
	ds_read_b128 v[146:149], v162
	ds_read_b128 v[154:157], v162 offset:1024
	ds_read_b128 v[158:161], v162 offset:2048
	ds_read_b128 v[162:165], v162 offset:3072
	s_add_u32 s24, s24, 0x40000
	s_addc_u32 s25, s25, 0
	s_mov_b32 m0, s31
	v_lshl_add_u64 v[206:207], s[24:25], 0, v[134:135]
	ds_read_b128 v[166:169], v174 offset:32768
	ds_read_b128 v[178:181], v174 offset:33792
	ds_read_b128 v[182:185], v174 offset:34816
	ds_read_b128 v[186:189], v174 offset:35840
	ds_read_b128 v[190:193], v174 offset:36864
	ds_read_b128 v[194:197], v174 offset:37888
	ds_read_b128 v[198:201], v174 offset:38912
	ds_read_b128 v[202:205], v174 offset:39936
	global_load_lds_dwordx4 v[206:207], off
	v_lshl_add_u64 v[206:207], s[24:25], 0, v[130:131]
	s_mov_b32 m0, s33
	s_nop 0
	global_load_lds_dwordx4 v[206:207], off
	s_waitcnt lgkmcnt(8)
	s_barrier
	s_waitcnt lgkmcnt(0)
	s_setprio 1
	s_waitcnt lgkmcnt(0)
	v_mfma_f32_16x16x32_bf16 v[124:127], v[146:149], v[166:169], v[124:127]
	v_mfma_f32_16x16x32_bf16 v[120:123], v[158:161], v[166:169], v[120:123]
	v_mfma_f32_16x16x32_bf16 v[112:115], v[146:149], v[182:185], v[112:115]
	v_mfma_f32_16x16x32_bf16 v[104:107], v[158:161], v[182:185], v[104:107]
	v_mfma_f32_16x16x32_bf16 v[92:95], v[146:149], v[190:193], v[92:95]
	v_mfma_f32_16x16x32_bf16 v[88:91], v[158:161], v[190:193], v[88:91]
	v_mfma_f32_16x16x32_bf16 v[80:83], v[146:149], v[198:201], v[80:83]
	v_mfma_f32_16x16x32_bf16 v[72:75], v[158:161], v[198:201], v[72:75]
	v_mfma_f32_16x16x32_bf16 v[124:127], v[154:157], v[178:181], v[124:127]
	v_mfma_f32_16x16x32_bf16 v[120:123], v[162:165], v[178:181], v[120:123]
	v_mfma_f32_16x16x32_bf16 v[112:115], v[154:157], v[186:189], v[112:115]
	v_mfma_f32_16x16x32_bf16 v[104:107], v[162:165], v[186:189], v[104:107]
	v_mfma_f32_16x16x32_bf16 v[92:95], v[154:157], v[194:197], v[92:95]
	v_mfma_f32_16x16x32_bf16 v[88:91], v[162:165], v[194:197], v[88:91]
	v_mfma_f32_16x16x32_bf16 v[80:83], v[154:157], v[202:205], v[80:83]
	v_mfma_f32_16x16x32_bf16 v[72:75], v[162:165], v[202:205], v[72:75]
	s_setprio 0
	s_barrier
	s_add_i32 s24, 0, 0x1c000
	s_add_i32 s25, s48, s27
	v_add_u32_e32 v177, s24, v171
	v_lshl_add_u64 v[150:151], v[150:151], 0, s[4:5]
	s_mov_b32 m0, s25
	ds_read_b128 v[206:209], v177
	ds_read_b128 v[210:213], v177 offset:1024
	ds_read_b128 v[214:217], v177 offset:2048
	ds_read_b128 v[218:221], v177 offset:3072
	global_load_lds_dwordx4 v[150:151], off
	v_lshl_add_u64 v[150:151], v[222:223], 0, s[4:5]
	s_add_i32 m0, s25, 0x2000
	s_nop 0
	global_load_lds_dwordx4 v[150:151], off
	s_barrier
	s_waitcnt lgkmcnt(0)
	s_setprio 1
	s_waitcnt lgkmcnt(0)
	v_mfma_f32_16x16x32_bf16 v[116:119], v[206:209], v[166:169], v[116:119]
	v_mfma_f32_16x16x32_bf16 v[108:111], v[214:217], v[166:169], v[108:111]
	v_mfma_f32_16x16x32_bf16 v[100:103], v[206:209], v[182:185], v[100:103]
	v_mfma_f32_16x16x32_bf16 v[96:99], v[214:217], v[182:185], v[96:99]
	v_mfma_f32_16x16x32_bf16 v[84:87], v[206:209], v[190:193], v[84:87]
	v_mfma_f32_16x16x32_bf16 v[76:79], v[214:217], v[190:193], v[76:79]
	v_mfma_f32_16x16x32_bf16 v[68:71], v[206:209], v[198:201], v[68:71]
	v_mfma_f32_16x16x32_bf16 v[64:67], v[214:217], v[198:201], v[64:67]
	v_mfma_f32_16x16x32_bf16 v[116:119], v[210:213], v[178:181], v[116:119]
	v_mfma_f32_16x16x32_bf16 v[108:111], v[218:221], v[178:181], v[108:111]
	v_mfma_f32_16x16x32_bf16 v[100:103], v[210:213], v[186:189], v[100:103]
	v_mfma_f32_16x16x32_bf16 v[96:99], v[218:221], v[186:189], v[96:99]
	v_mfma_f32_16x16x32_bf16 v[84:87], v[210:213], v[194:197], v[84:87]
	v_mfma_f32_16x16x32_bf16 v[76:79], v[218:221], v[194:197], v[76:79]
	v_mfma_f32_16x16x32_bf16 v[68:71], v[210:213], v[202:205], v[68:71]
	v_mfma_f32_16x16x32_bf16 v[64:67], v[218:221], v[202:205], v[64:67]
	s_setprio 0
	s_mov_b32 m0, s35
	v_lshl_add_u64 v[150:151], v[224:225], 0, s[4:5]
	s_barrier
	ds_read_b128 v[166:169], v174 offset:49152
	ds_read_b128 v[178:181], v174 offset:50176
	ds_read_b128 v[182:185], v174 offset:51200
	ds_read_b128 v[186:189], v174 offset:52224
	ds_read_b128 v[190:193], v174 offset:53248
	ds_read_b128 v[194:197], v174 offset:54272
	ds_read_b128 v[198:201], v174 offset:55296
	ds_read_b128 v[202:205], v174 offset:56320
	global_load_lds_dwordx4 v[150:151], off
	v_lshl_add_u64 v[150:151], v[226:227], 0, s[4:5]
	s_mov_b32 m0, s36
	s_nop 0
	global_load_lds_dwordx4 v[150:151], off
	s_barrier
;     __device__ __forceinline__ void operator()(const f32x4 (&acc)[2][2][4][2], const Unit& u, int wr, int wc, int fr, int fq, const float (&)[8]) const {
;     ...
;             for (int m = 0; m < 4; ++m) { const int row = row0 + ai * HALF + m * 16;
;                 if (SLOTS == 1) ep[ai * 4 + m] = ss[row];
;                 else { const f32x4 pq = *(const f32x4*)(ss + (size_t)row * 16 + 4 * fq); ep[ai * 4 + m] = (pq[0] + pq[1]) + (pq[2] + pq[3]); } }
;         if (SLOTS != 1) {
; #pragma unroll
;             for (int q = 0; q < 8; ++q) { ep[q] += __shfl_xor(ep[q], 16); ep[q] += __shfl_xor(ep[q], 32); } }
;         if (DT && u.pn == 20) {
;             if (wc == 0) {
; #pragma unroll
;                 for (int ai = 0; ai < 2; ++ai)
; #pragma unroll
;                     for (int m = 0; m < 4; ++m) { const int row = row0 + ai * HALF + m * 16; const float rs = rsqrtf(ep[ai * 4 + m] * (1.0f / 1024.0f) + EPS);
;                         *(f32x4*)(dt + (size_t)row * 32 + 8 * fq) = acc[ai][0][m][0] * rs; *(f32x4*)(dt + (size_t)row * 32 + 8 * fq + 4) = acc[ai][0][m][1] * rs; }
;             }
;             return;
;         }
;         const int col0 = u.pn * BM + wc * 32 + 8 * fq;
; #pragma unroll
;         for (int ai = 0; ai < 2; ++ai)
; #pragma unroll
;             for (int m = 0; m < 4; ++m) { const int row = row0 + ai * HALF + m * 16; const float rs = rsqrtf(ep[ai * 4 + m] * (1.0f / 1024.0f) + EPS);
;                 u16* rowp = O + (size_t)row * ldc + col0;
; #pragma unroll
;                 for (int bj = 0; bj < 2; ++bj) { f32x4 v0 = acc[ai][bj][m][0] * rs, v1 = acc[ai][bj][m][1] * rs;
;                     if (ACT == 1) {
; #pragma unroll
;                         for (int j = 0; j < 4; ++j) { const float a0 = fmaxf(v0[j], 0.f), a1 = fmaxf(v1[j], 0.f); v0[j] = a0 * a0; v1[j] = a1 * a1; } }
;                     u32x4 w; w.x = pk2(v0[0], v0[1]); w.y = pk2(v0[2], v0[3]); w.z = pk2(v1[0], v1[1]); w.w = pk2(v1[2], v1[3]);
;                     *(u32x4*)(rowp + bj * HALF) = w; } }
; template <class Epi>
; __device__ __forceinline__ void gemm_phase(LAS unsigned char* lds, const Gemm g, const StaticOrder& S, const Epi& E) {
;     ...
;             PG8_BAR; PG8_WAIT_L(0); PG8_MMA(1, 0, At, B0); PG8_BAR; PG8_SCHED;
;             PG8_STAGE(PG8_SB(1, 1), b3 + hstepB, voffB);
;             PG8_WAIT_V(6); PG8_BAR; PG8_MMA(1, 1, At, B1); PG8_BAR;
	s_waitcnt lgkmcnt(0)
	s_setprio 1
	s_waitcnt lgkmcnt(0)
	v_mfma_f32_16x16x32_bf16 v[60:63], v[146:149], v[166:169], v[60:63]
	v_mfma_f32_16x16x32_bf16 v[56:59], v[158:161], v[166:169], v[56:59]
	v_mfma_f32_16x16x32_bf16 v[48:51], v[146:149], v[182:185], v[48:51]
	v_mfma_f32_16x16x32_bf16 v[40:43], v[158:161], v[182:185], v[40:43]
	v_mfma_f32_16x16x32_bf16 v[32:35], v[146:149], v[190:193], v[32:35]
	v_mfma_f32_16x16x32_bf16 v[24:27], v[158:161], v[190:193], v[24:27]
	v_mfma_f32_16x16x32_bf16 v[16:19], v[146:149], v[198:201], v[16:19]
	v_mfma_f32_16x16x32_bf16 v[8:11], v[158:161], v[198:201], v[8:11]
	v_mfma_f32_16x16x32_bf16 v[60:63], v[154:157], v[178:181], v[60:63]
	v_mfma_f32_16x16x32_bf16 v[56:59], v[162:165], v[178:181], v[56:59]
	v_mfma_f32_16x16x32_bf16 v[48:51], v[154:157], v[186:189], v[48:51]
	v_mfma_f32_16x16x32_bf16 v[40:43], v[162:165], v[186:189], v[40:43]
	v_mfma_f32_16x16x32_bf16 v[32:35], v[154:157], v[194:197], v[32:35]
	v_mfma_f32_16x16x32_bf16 v[24:27], v[162:165], v[194:197], v[24:27]
	v_mfma_f32_16x16x32_bf16 v[16:19], v[154:157], v[202:205], v[16:19]
	v_mfma_f32_16x16x32_bf16 v[8:11], v[162:165], v[202:205], v[8:11]
	s_setprio 0
	s_barrier
	s_add_u32 s22, s22, 0x40080
	s_addc_u32 s23, s23, 0
	s_add_i32 s24, s24, s27
	v_lshl_add_u64 v[146:147], s[22:23], 0, v[132:133]
	s_mov_b32 m0, s24
	s_nop 0
	global_load_lds_dwordx4 v[146:147], off
	v_lshl_add_u64 v[146:147], s[22:23], 0, v[128:129]
	s_add_i32 m0, s24, 0x2000
	s_nop 0
	global_load_lds_dwordx4 v[146:147], off
	s_waitcnt vmcnt(6)
	s_barrier
	s_setprio 1
	v_mfma_f32_16x16x32_bf16 v[52:55], v[206:209], v[166:169], v[52:55]
	v_mfma_f32_16x16x32_bf16 v[44:47], v[214:217], v[166:169], v[44:47]
	v_mfma_f32_16x16x32_bf16 v[36:39], v[206:209], v[182:185], v[36:39]
	v_mfma_f32_16x16x32_bf16 v[28:31], v[214:217], v[182:185], v[28:31]
	v_mfma_f32_16x16x32_bf16 v[20:23], v[206:209], v[190:193], v[20:23]
	v_mfma_f32_16x16x32_bf16 v[12:15], v[214:217], v[190:193], v[12:15]
	v_mfma_f32_16x16x32_bf16 v[4:7], v[206:209], v[198:201], v[4:7]
	v_mfma_f32_16x16x32_bf16 v[0:3], v[214:217], v[198:201], v[0:3]
	v_mfma_f32_16x16x32_bf16 v[52:55], v[210:213], v[178:181], v[52:55]
	v_mfma_f32_16x16x32_bf16 v[44:47], v[218:221], v[178:181], v[44:47]
	v_mfma_f32_16x16x32_bf16 v[36:39], v[210:213], v[186:189], v[36:39]
	v_mfma_f32_16x16x32_bf16 v[28:31], v[218:221], v[186:189], v[28:31]
	v_mfma_f32_16x16x32_bf16 v[20:23], v[210:213], v[194:197], v[20:23]
	v_mfma_f32_16x16x32_bf16 v[12:15], v[218:221], v[194:197], v[12:15]
	v_mfma_f32_16x16x32_bf16 v[4:7], v[210:213], v[202:205], v[4:7]
	v_mfma_f32_16x16x32_bf16 v[0:3], v[218:221], v[202:205], v[0:3]
	s_setprio 0
	s_add_i32 s47, s47, 2
	s_add_u32 s20, s20, 0x100
	s_addc_u32 s21, s21, 0
	s_add_u32 s45, s45, 0x100
	s_addc_u32 s46, s46, 0
	s_cmp_gt_u32 s47, 13
	s_barrier
	s_cbranch_scc0 .LBB0_922
	s_bfe_u32 vcc_lo, s18, 0x20003
	s_lshl_b32 vcc_lo, vcc_lo, 10
	s_add_i32 vcc_lo, vcc_lo, 0x20010
	v_lshl_add_u32 v236, v170, 2, vcc_lo
	ds_read_b32 v228, v236
	ds_read_b32 v229, v236 offset:64
	ds_read_b32 v230, v236 offset:128
	ds_read_b32 v231, v236 offset:192
	ds_read_b32 v232, v236 offset:512
	ds_read_b32 v233, v236 offset:576
	ds_read_b32 v234, v236 offset:640
	ds_read_b32 v235, v236 offset:704
	s_waitcnt lgkmcnt(0)
	v_lshl_add_u32 v154, s18, 8, v170
	v_or_b32_e32 v206, 16, v154
	v_or_b32_e32 v168, 32, v154
	v_or_b32_e32 v162, 48, v154
	v_add_u32_e32 v160, 0x80, v154
	v_add_u32_e32 v156, 0x90, v154
	v_add_u32_e32 v150, 0xa0, v154
	v_add_u32_e32 v146, 0xb0, v154
	v_lshl_or_b32 v208, s42, 8, v172
	v_mov_b64_e32 v[148:149], s[96:97]
	v_ashrrev_i32_e32 v209, 31, v208
	v_mad_i64_i32 v[210:211], s[20:21], v154, s40, v[148:149]
	s_nop 0
	v_lshlrev_b64 v[154:155], 1, v[208:209]
	v_lshl_add_u64 v[208:209], v[210:211], 0, v[154:155]
	s_mov_b32 s42, s10
	s_mov_b32 s18, s12
	s_mov_b64 s[22:23], s[16:17]
	s_waitcnt vmcnt(8)
	s_waitcnt lgkmcnt(0)
	s_waitcnt lgkmcnt(0)
	v_mov_b32_e32 v178, v228
	v_pk_mul_f32 v[126:127], v[126:127], v[178:179] op_sel_hi:[1,0]
	v_pk_mul_f32 v[124:125], v[124:125], v[178:179] op_sel_hi:[1,0]
	v_pk_mul_f32 v[190:191], v[122:123], v[178:179] op_sel_hi:[1,0]
	v_pk_mul_f32 v[122:123], v[120:121], v[178:179] op_sel_hi:[1,0]
	v_cvt_pk_bf16_f32 v120, v124, v125
	v_cvt_pk_bf16_f32 v121, v126, v127
	v_cvt_pk_bf16_f32 v122, v122, v123
	v_cvt_pk_bf16_f32 v123, v190, v191
	v_pk_mul_f32 v[116:117], v[116:117], v[178:179] op_sel_hi:[1,0]
	global_store_dwordx4 v[208:209], v[120:123], off
	s_nop 0
	v_pk_mul_f32 v[118:119], v[118:119], v[178:179] op_sel_hi:[1,0]
	v_pk_mul_f32 v[120:121], v[110:111], v[178:179] op_sel_hi:[1,0]
	v_pk_mul_f32 v[110:111], v[108:109], v[178:179] op_sel_hi:[1,0]
	v_cvt_pk_bf16_f32 v108, v116, v117
	v_cvt_pk_bf16_f32 v109, v118, v119
	v_cvt_pk_bf16_f32 v110, v110, v111
	v_cvt_pk_bf16_f32 v111, v120, v121
	global_store_dwordx4 v[208:209], v[108:111], off offset:256
	s_nop 1
	v_mov_b32_e32 v108, v229
	v_mad_i64_i32 v[110:111], s[20:21], v206, s40, v[148:149]
	v_pk_mul_f32 v[114:115], v[114:115], v[108:109] op_sel_hi:[1,0]
	v_pk_mul_f32 v[112:113], v[112:113], v[108:109] op_sel_hi:[1,0]
	v_pk_mul_f32 v[116:117], v[106:107], v[108:109] op_sel_hi:[1,0]
	v_pk_mul_f32 v[106:107], v[104:105], v[108:109] op_sel_hi:[1,0]
	v_lshl_add_u64 v[110:111], v[110:111], 0, v[154:155]
	v_cvt_pk_bf16_f32 v104, v112, v113
	v_cvt_pk_bf16_f32 v105, v114, v115
	v_cvt_pk_bf16_f32 v106, v106, v107
	v_cvt_pk_bf16_f32 v107, v116, v117
	global_store_dwordx4 v[110:111], v[104:107], off
	v_pk_mul_f32 v[100:101], v[100:101], v[108:109] op_sel_hi:[1,0]
	v_pk_mul_f32 v[112:113], v[98:99], v[108:109] op_sel_hi:[1,0]
	v_pk_mul_f32 v[98:99], v[96:97], v[108:109] op_sel_hi:[1,0]
	v_cvt_pk_bf16_f32 v96, v100, v101
	v_pk_mul_f32 v[102:103], v[102:103], v[108:109] op_sel_hi:[1,0]
	v_cvt_pk_bf16_f32 v98, v98, v99
	s_waitcnt lgkmcnt(0)
; __device__ __forceinline__ unsigned pk2(float lo, float hi) { const f32x2 v = (f32x2){lo, hi}; const bf16x2_t b = __builtin_convertvector(v, bf16x2_t); return __builtin_bit_cast(unsigned, b); }
; #define PG8_WAIT_V(n) asm volatile("s_waitcnt vmcnt(" #n ")" ::: "memory")
; #define PG8_BAR __builtin_amdgcn_s_barrier()
;     __device__ __forceinline__ void operator()(const f32x4 (&acc)[2][2][4][2], const Unit& u, int wr, int wc, int fr, int fq, const float (&)[8]) const {
;     ...
;             for (int m = 0; m < 4; ++m) { const int row = row0 + ai * HALF + m * 16; const float rs = rsqrtf(ep[ai * 4 + m] * (1.0f / 1024.0f) + EPS);
;                 u16* rowp = O + (size_t)row * ldc + col0;
; #pragma unroll
;                 for (int bj = 0; bj < 2; ++bj) { f32x4 v0 = acc[ai][bj][m][0] * rs, v1 = acc[ai][bj][m][1] * rs;
;                     if (ACT == 1) {
; #pragma unroll
;                         for (int j = 0; j < 4; ++j) { const float a0 = fmaxf(v0[j], 0.f), a1 = fmaxf(v1[j], 0.f); v0[j] = a0 * a0; v1[j] = a1 * a1; } }
;                     u32x4 w; w.x = pk2(v0[0], v0[1]); w.y = pk2(v0[2], v0[3]); w.z = pk2(v1[0], v1[1]); w.w = pk2(v1[2], v1[3]);
;                     *(u32x4*)(rowp + bj * HALF) = w; } }
; template <class Epi>
; __device__ __forceinline__ void gemm_phase(LAS unsigned char* lds, const Gemm g, const StaticOrder& S, const Epi& E) {
;     ...
;         cur = nxt; cA = nA; cB = nB; ++ui;
;     }
;     PG8_WAIT_V(0);
;     if (wr == 0) PG8_BAR;
;     PG8_BAR;
	v_cvt_pk_bf16_f32 v97, v102, v103
	v_cvt_pk_bf16_f32 v99, v112, v113
	global_store_dwordx4 v[110:111], v[96:99], off offset:256
	s_nop 0
	s_waitcnt lgkmcnt(0)
	v_mad_i64_i32 v[98:99], s[20:21], v168, s40, v[148:149]
	v_lshl_add_u64 v[98:99], v[98:99], 0, v[154:155]
	v_mov_b32_e32 v100, v230
	v_pk_mul_f32 v[94:95], v[94:95], v[100:101] op_sel_hi:[1,0]
	v_pk_mul_f32 v[92:93], v[92:93], v[100:101] op_sel_hi:[1,0]
	v_pk_mul_f32 v[102:103], v[90:91], v[100:101] op_sel_hi:[1,0]
	v_pk_mul_f32 v[90:91], v[88:89], v[100:101] op_sel_hi:[1,0]
	v_cvt_pk_bf16_f32 v88, v92, v93
	v_cvt_pk_bf16_f32 v89, v94, v95
	v_cvt_pk_bf16_f32 v90, v90, v91
	v_cvt_pk_bf16_f32 v91, v102, v103
	v_pk_mul_f32 v[84:85], v[84:85], v[100:101] op_sel_hi:[1,0]
	global_store_dwordx4 v[98:99], v[88:91], off
	s_nop 0
	v_pk_mul_f32 v[86:87], v[86:87], v[100:101] op_sel_hi:[1,0]
	v_pk_mul_f32 v[88:89], v[78:79], v[100:101] op_sel_hi:[1,0]
	v_pk_mul_f32 v[78:79], v[76:77], v[100:101] op_sel_hi:[1,0]
	v_cvt_pk_bf16_f32 v76, v84, v85
	v_cvt_pk_bf16_f32 v77, v86, v87
	v_cvt_pk_bf16_f32 v78, v78, v79
	v_cvt_pk_bf16_f32 v79, v88, v89
	global_store_dwordx4 v[98:99], v[76:79], off offset:256
	s_nop 1
	v_mov_b32_e32 v76, v231
	v_mad_i64_i32 v[78:79], s[20:21], v162, s40, v[148:149]
	v_pk_mul_f32 v[82:83], v[82:83], v[76:77] op_sel_hi:[1,0]
	v_pk_mul_f32 v[80:81], v[80:81], v[76:77] op_sel_hi:[1,0]
	v_pk_mul_f32 v[84:85], v[74:75], v[76:77] op_sel_hi:[1,0]
	v_pk_mul_f32 v[74:75], v[72:73], v[76:77] op_sel_hi:[1,0]
	v_lshl_add_u64 v[78:79], v[78:79], 0, v[154:155]
	v_cvt_pk_bf16_f32 v72, v80, v81
	v_cvt_pk_bf16_f32 v73, v82, v83
	v_cvt_pk_bf16_f32 v74, v74, v75
	v_cvt_pk_bf16_f32 v75, v84, v85
	global_store_dwordx4 v[78:79], v[72:75], off
	v_pk_mul_f32 v[68:69], v[68:69], v[76:77] op_sel_hi:[1,0]
	v_pk_mul_f32 v[80:81], v[66:67], v[76:77] op_sel_hi:[1,0]
	v_pk_mul_f32 v[66:67], v[64:65], v[76:77] op_sel_hi:[1,0]
	v_cvt_pk_bf16_f32 v64, v68, v69
	v_pk_mul_f32 v[70:71], v[70:71], v[76:77] op_sel_hi:[1,0]
	v_cvt_pk_bf16_f32 v66, v66, v67
	s_waitcnt lgkmcnt(0)
	v_cvt_pk_bf16_f32 v65, v70, v71
	v_cvt_pk_bf16_f32 v67, v80, v81
	global_store_dwordx4 v[78:79], v[64:67], off offset:256
	s_waitcnt lgkmcnt(0)
	s_nop 0
	s_nop 0
	s_nop 0
	s_nop 1
	v_mad_i64_i32 v[66:67], s[20:21], v160, s40, v[148:149]
	v_lshl_add_u64 v[66:67], v[66:67], 0, v[154:155]
	v_mov_b32_e32 v68, v232
	v_pk_mul_f32 v[62:63], v[62:63], v[68:69] op_sel_hi:[1,0]
	v_pk_mul_f32 v[60:61], v[60:61], v[68:69] op_sel_hi:[1,0]
	v_pk_mul_f32 v[70:71], v[58:59], v[68:69] op_sel_hi:[1,0]
	v_pk_mul_f32 v[58:59], v[56:57], v[68:69] op_sel_hi:[1,0]
	v_cvt_pk_bf16_f32 v56, v60, v61
	v_cvt_pk_bf16_f32 v57, v62, v63
	v_cvt_pk_bf16_f32 v58, v58, v59
	v_cvt_pk_bf16_f32 v59, v70, v71
	v_pk_mul_f32 v[52:53], v[52:53], v[68:69] op_sel_hi:[1,0]
	global_store_dwordx4 v[66:67], v[56:59], off
	s_nop 0
	v_pk_mul_f32 v[54:55], v[54:55], v[68:69] op_sel_hi:[1,0]
	v_pk_mul_f32 v[56:57], v[46:47], v[68:69] op_sel_hi:[1,0]
	v_pk_mul_f32 v[46:47], v[44:45], v[68:69] op_sel_hi:[1,0]
	v_cvt_pk_bf16_f32 v44, v52, v53
	v_cvt_pk_bf16_f32 v45, v54, v55
	v_cvt_pk_bf16_f32 v46, v46, v47
	v_cvt_pk_bf16_f32 v47, v56, v57
	global_store_dwordx4 v[66:67], v[44:47], off offset:256
	s_nop 1
	v_mov_b32_e32 v44, v233
	v_mad_i64_i32 v[46:47], s[20:21], v156, s40, v[148:149]
	v_pk_mul_f32 v[50:51], v[50:51], v[44:45] op_sel_hi:[1,0]
	v_pk_mul_f32 v[48:49], v[48:49], v[44:45] op_sel_hi:[1,0]
	v_pk_mul_f32 v[52:53], v[42:43], v[44:45] op_sel_hi:[1,0]
	v_pk_mul_f32 v[42:43], v[40:41], v[44:45] op_sel_hi:[1,0]
	v_lshl_add_u64 v[46:47], v[46:47], 0, v[154:155]
	v_cvt_pk_bf16_f32 v40, v48, v49
	v_cvt_pk_bf16_f32 v41, v50, v51
	v_cvt_pk_bf16_f32 v42, v42, v43
	v_cvt_pk_bf16_f32 v43, v52, v53
	global_store_dwordx4 v[46:47], v[40:43], off
	v_pk_mul_f32 v[36:37], v[36:37], v[44:45] op_sel_hi:[1,0]
	v_pk_mul_f32 v[48:49], v[30:31], v[44:45] op_sel_hi:[1,0]
	v_pk_mul_f32 v[30:31], v[28:29], v[44:45] op_sel_hi:[1,0]
	v_cvt_pk_bf16_f32 v28, v36, v37
	v_pk_mul_f32 v[38:39], v[38:39], v[44:45] op_sel_hi:[1,0]
	v_cvt_pk_bf16_f32 v30, v30, v31
	s_waitcnt lgkmcnt(0)
	v_cvt_pk_bf16_f32 v29, v38, v39
	v_cvt_pk_bf16_f32 v31, v48, v49
	global_store_dwordx4 v[46:47], v[28:31], off offset:256
	s_waitcnt lgkmcnt(0)
	s_nop 0
	s_nop 0
	s_nop 0
	s_nop 1
	v_mad_i64_i32 v[30:31], s[20:21], v150, s40, v[148:149]
	v_lshl_add_u64 v[30:31], v[30:31], 0, v[154:155]
	v_mov_b32_e32 v36, v234
	v_pk_mul_f32 v[34:35], v[34:35], v[36:37] op_sel_hi:[1,0]
	v_pk_mul_f32 v[32:33], v[32:33], v[36:37] op_sel_hi:[1,0]
	v_pk_mul_f32 v[38:39], v[26:27], v[36:37] op_sel_hi:[1,0]
	v_pk_mul_f32 v[26:27], v[24:25], v[36:37] op_sel_hi:[1,0]
	v_cvt_pk_bf16_f32 v24, v32, v33
	v_cvt_pk_bf16_f32 v25, v34, v35
	v_cvt_pk_bf16_f32 v26, v26, v27
	v_cvt_pk_bf16_f32 v27, v38, v39
	v_pk_mul_f32 v[20:21], v[20:21], v[36:37] op_sel_hi:[1,0]
	global_store_dwordx4 v[30:31], v[24:27], off
	s_nop 0
	v_pk_mul_f32 v[22:23], v[22:23], v[36:37] op_sel_hi:[1,0]
	v_pk_mul_f32 v[24:25], v[14:15], v[36:37] op_sel_hi:[1,0]
	v_pk_mul_f32 v[14:15], v[12:13], v[36:37] op_sel_hi:[1,0]
	v_cvt_pk_bf16_f32 v12, v20, v21
	v_cvt_pk_bf16_f32 v13, v22, v23
	v_cvt_pk_bf16_f32 v14, v14, v15
	v_cvt_pk_bf16_f32 v15, v24, v25
	global_store_dwordx4 v[30:31], v[12:15], off offset:256
	s_nop 1
	v_mov_b32_e32 v12, v235
	v_mad_i64_i32 v[14:15], s[20:21], v146, s40, v[148:149]
	v_pk_mul_f32 v[18:19], v[18:19], v[12:13] op_sel_hi:[1,0]
	v_pk_mul_f32 v[16:17], v[16:17], v[12:13] op_sel_hi:[1,0]
	v_pk_mul_f32 v[20:21], v[10:11], v[12:13] op_sel_hi:[1,0]
	v_pk_mul_f32 v[10:11], v[8:9], v[12:13] op_sel_hi:[1,0]
	v_lshl_add_u64 v[14:15], v[14:15], 0, v[154:155]
	v_cvt_pk_bf16_f32 v8, v16, v17
	v_cvt_pk_bf16_f32 v9, v18, v19
	v_cvt_pk_bf16_f32 v10, v10, v11
	v_cvt_pk_bf16_f32 v11, v20, v21
	global_store_dwordx4 v[14:15], v[8:11], off
	v_pk_mul_f32 v[6:7], v[6:7], v[12:13] op_sel_hi:[1,0]
	v_pk_mul_f32 v[4:5], v[4:5], v[12:13] op_sel_hi:[1,0]
	v_pk_mul_f32 v[8:9], v[2:3], v[12:13] op_sel_hi:[1,0]
	v_pk_mul_f32 v[2:3], v[0:1], v[12:13] op_sel_hi:[1,0]
	v_cvt_pk_bf16_f32 v0, v4, v5
	v_cvt_pk_bf16_f32 v1, v6, v7
	v_cvt_pk_bf16_f32 v2, v2, v3
	v_cvt_pk_bf16_f32 v3, v8, v9
	s_and_b64 vcc, exec, s[0:1]
	s_mov_b64 s[20:21], s[14:15]
	global_store_dwordx4 v[14:15], v[0:3], off offset:256
	s_cbranch_vccz .LBB0_919
	s_waitcnt vmcnt(0)
	v_readlane_b32 s40, v251, 54
	s_cmpk_gt_u32 s7, 0xff
	v_readlane_b32 s41, v251, 55
	s_cbranch_scc1 .LBB0_926
	s_barrier
